# K-loops (P1, P4): per-segment s_setprio flips deleted, one static s_setprio 1 for waves 4-7 before the unit loops
# baseline (speedup 1.0000x reference)
; #define PG8_BAR __builtin_amdgcn_s_barrier()
; template <class Epi, class Sched, bool ALIGN_EPI = false, bool SP2 = false>
; __device__ __forceinline__ void gemm_phase(PG8_LAS unsigned char* lds, const Gemm g, const Sched& S, const Epi& E) {
;     ...
;         PG8_STAGE(PG8_SB(1, 0), cB + kstep, voffB); PG8_STAGE(PG8_SA(1, 0), cA + kstep, voffA); PG8_STAGE(PG8_SB(1, 1), cB + hstep + kstep, voffB);
;         PG8_WAIT_V(6); PG8_BAR;
;     __device__ __forceinline__ void operator()(const f32x4 (&acc)[2][2][4][2], const pg8::Unit& u, int wr, int wc, int fr, int fq) const {
;         const int sec = u.pn >> 1, half = u.pn & 1;
;         bf16_t* base = proj + (size_t)sec * SEC_STRIDE;
;         const int row0 = u.pm * 256 + wr * 64 + fr;
;         if (sec <= 1) {
;             const float* gn = sec == 0 ? qg : kg; const float osc = sec == 0 ? 0.125f * LOG2E : 1.f;
;             f32x4 g[2][2];
; #pragma unroll
;             for (int bj = 0; bj < 2; ++bj)
; #pragma unroll
;                 for (int n = 0; n < 2; ++n) g[bj][n] = *(const f32x4*)(gn + 32 * bj + 8 * fq + 4 * n);
;             const int col0 = 256 * half + 64 * wc + 8 * fq;
; #pragma unroll
;             for (int ai = 0; ai < 2; ++ai)
; #pragma unroll
;                 for (int m = 0; m < 4; ++m) {
;                     float ss = 0.f;
; #pragma unroll
;                     for (int bj = 0; bj < 2; ++bj)
; #pragma unroll
;                         for (int n = 0; n < 2; ++n) { const f32x4 x = acc[ai][bj][m][n]; ss += (x[0] * x[0] + x[1] * x[1]) + (x[2] * x[2] + x[3] * x[3]); }
;                     ss = row4_sum(ss);
;                     const float r = rsqrtf(ss * (1.f / 64.f) + EPS) * osc;
;                     bf16_t* rowp = base + (size_t)(row0 + ai * 128 + m * 16) * 512 + col0;
; #pragma unroll
;                     for (int bj = 0; bj < 2; ++bj) { const f32x4 v0 = acc[ai][bj][m][0] * r * g[bj][0], v1 = acc[ai][bj][m][1] * r * g[bj][1];
;                         u32x4 w; w.x = cvt_pk_bf16(v0[0], v0[1]); w.y = cvt_pk_bf16(v0[2], v0[3]); w.z = cvt_pk_bf16(v1[0], v1[1]); w.w = cvt_pk_bf16(v1[2], v1[3]);
;                         *(u32x4*)(rowp + 32 * bj) = w; }
;                 }
;         } else if (sec == 4 || sec == 5) {
;             const float osc = sec == 5 ? 0.08838834764831845f : 1.f;
;             const int col0 = 256 * half + 128 * (wc >> 1) + 32 * (wc & 1) + 8 * fq, i0 = 32 * (wc & 1) + 8 * fq;
.LBB0_156:
	s_add_u32 s78, s22, 0xc000000
	s_mov_b64 s[12:13], 0x80
	s_addc_u32 s79, s23, 0
	s_and_b32 s5, s1, 3
	s_add_i32 m0, s47, 0x18000
	v_lshl_add_u64 v[10:11], v[10:11], 0, s[12:13]
	s_ashr_i32 s80, s3, 31
	s_ashr_i32 s81, s2, 31
	s_lshl_b32 s15, s0, 13
	s_lshl_b32 s1, s1, 5
	s_lshl_b32 s18, s5, 12
	s_waitcnt vmcnt(2)
	s_barrier
	global_load_lds_dwordx4 v[10:11], off
	v_lshl_add_u64 v[8:9], v[8:9], 0, s[12:13]
	s_add_i32 m0, s47, 0x1a000
	s_add_i32 s82, s47, 0x8000
	s_add_i32 s83, s47, 0xa000
	global_load_lds_dwordx4 v[8:9], off
	v_lshl_add_u64 v[4:5], v[4:5], 0, s[12:13]
	s_mov_b32 m0, s82
	s_add_u32 s16, s50, 0x40080
	global_load_lds_dwordx4 v[4:5], off
	v_lshl_add_u64 v[4:5], v[6:7], 0, s[12:13]
	s_mov_b32 m0, s83
	s_addc_u32 s17, s51, 0
	global_load_lds_dwordx4 v[4:5], off
	s_add_i32 m0, s47, 0x1c000
	v_lshl_add_u64 v[4:5], s[16:17], 0, v[148:149]
	global_load_lds_dwordx4 v[4:5], off
	v_lshl_add_u64 v[4:5], s[16:17], 0, v[152:153]
	s_add_i32 m0, s47, 0x1e000
	v_lshlrev_b32_e32 v1, 6, v0
	global_load_lds_dwordx4 v[4:5], off
	v_lshlrev_b32_e32 v5, 1, v2
	s_movk_i32 s16, 0x3c0
	v_and_b32_e32 v4, 15, v0
	v_and_or_b32 v6, v1, s16, v5
	v_lshlrev_b32_e32 v1, 2, v0
	v_and_b32_e32 v7, 32, v1
	v_lshl_or_b32 v1, s0, 6, v4
	v_lshl_or_b32 v4, v4, 6, v5
	s_cmpk_lt_u32 s14, 0x100
	v_bitop3_b32 v8, v4, s15, v7 bitop3:0xde
	s_cselect_b64 s[14:15], -1, 0
	s_and_b32 s17, s1, 32
	v_or_b32_e32 v4, s17, v2
	v_lshlrev_b32_e32 v154, 2, v4
	v_lshl_add_u64 v[4:5], s[22:23], 0, v[154:155]
	s_mov_b64 s[0:1], 0x100000
	v_lshl_add_u64 v[156:157], v[4:5], 0, s[0:1]
	s_mov_b64 s[0:1], 0x500000
	v_lshl_add_u64 v[158:159], v[4:5], 0, s[0:1]
	s_mov_b64 s[0:1], 0x101000
	v_lshl_add_u64 v[160:161], v[4:5], 0, s[0:1]
	s_mov_b64 s[0:1], 0x501000
	v_lshl_add_u64 v[162:163], v[4:5], 0, s[0:1]
	v_lshlrev_b32_e32 v5, 8, v0
	v_bitop3_b32 v181, s18, v6, v7 bitop3:0xf6
	v_and_b32_e32 v5, 0x18000, v5
	v_lshlrev_b32_e32 v6, 11, v13
	s_lshl_b32 s5, s5, 6
	v_or3_b32 v5, v3, v5, v6
	s_and_b32 s16, s5, 0x80
	v_add_u32_e32 v164, v5, v12
	v_lshlrev_b32_e32 v5, 4, v14
	s_waitcnt vmcnt(6)
	s_or_b32 s0, s16, s17
	v_and_b32_e32 v5, 0x38000, v5
	v_or_b32_e32 v4, s0, v2
	v_or3_b32 v3, v3, v5, v6
	s_add_i32 s85, 0, 0x10000
	s_add_i32 s86, 0, 0x14000
	v_or_b32_e32 v182, s5, v2
	v_mov_b32_e32 v165, v155
	v_add_u32_e32 v166, v3, v12
	v_mov_b32_e32 v167, v155
	v_mov_b64_e32 v[168:169], 0x1400
	v_mov_b64_e32 v[170:171], 0x13ff
	s_movk_i32 s84, 0x281
	v_add_u32_e32 v183, s85, v181
	v_add_u32_e32 v184, s86, v181
	v_add_u32_e32 v185, 0, v8
	s_mov_b64 s[16:17], 0x20000
	s_mov_b32 s87, 0x20000
	s_mov_b64 s[18:19], 0x24000
	s_mov_b32 s88, 0x24000
	s_mov_b64 s[20:21], 0x28000
	s_mov_b32 s89, 0x28000
	s_mov_b64 s[24:25], 0x2c000
	s_mov_b32 s90, 0x2c000
	v_lshlrev_b32_e32 v186, 1, v4
	v_lshlrev_b32_e32 v187, 2, v2
	v_mov_b32_e32 v188, 0x358637bd
	s_mov_b32 s91, 0x800000
	v_mov_b32_e32 v189, 0x3db504f3
	v_mov_b32_e32 v190, 0x3e38aa3b
	s_barrier
	s_cmp_ge_u32 s97, 4
	s_cbranch_scc0 .Lp1_prio
	s_setprio 1
.Lp1_prio:
	s_branch .LBB0_159

; #define PG8_STAGE(bufoff, gbase, voff) do { _Pragma("unroll") for (int _i = 0; _i < 2; ++_i) \
;         __builtin_amdgcn_global_load_lds((const unsigned*)((const char*)(gbase) + (voff)[_i]), (PG8_LAS unsigned*)(lds + (bufoff) + ldsw + _i * 8192), 16, 0, 0); } while (0)
; #define PG8_LDA(dst, b, h) do { _Pragma("unroll") for (int m = 0; m < 4; ++m) _Pragma("unroll") for (int k = 0; k < 2; ++k) dst[m][k] = *(const PG8_LAS bf16x8*)(lds + PG8_SA(b, h) + aoff + m * 2048 + k * 1024); } while (0)
; #define PG8_LDB(dst, b, h) do { _Pragma("unroll") for (int n = 0; n < 2; ++n) _Pragma("unroll") for (int k = 0; k < 2; ++k) dst[n][k] = *(const PG8_LAS bf16x8*)(lds + PG8_SB(b, h) + boff + n * 2048 + k * 1024); } while (0)
; #define PG8_MMA(ai, bj, At, Bt) do { __builtin_amdgcn_s_setprio(1); _Pragma("unroll") for (int m = 0; m < 4; ++m) _Pragma("unroll") for (int n = 0; n < 2; ++n) _Pragma("unroll") for (int k = 0; k < 2; ++k) \
;         acc[ai][bj][m][n] = __builtin_amdgcn_mfma_f32_16x16x32_bf16(Bt[n][k], At[m][k], acc[ai][bj][m][n], 0, 0, 0); __builtin_amdgcn_s_setprio(0); } while (0)
; #define PG8_WAIT_V(n) asm volatile("s_waitcnt vmcnt(" #n ")" ::: "memory")
; #define PG8_WAIT_L(n) asm volatile("s_waitcnt lgkmcnt(" #n ")" ::: "memory")
; #define PG8_BAR __builtin_amdgcn_s_barrier()
; #define PG8_SCHED __builtin_amdgcn_sched_barrier(0)
; template <class Epi, class Sched, bool ALIGN_EPI = false, bool SP2 = false>
; __device__ __forceinline__ void gemm_phase(PG8_LAS unsigned char* lds, const Gemm g, const Sched& S, const Epi& E) {
;     ...
;             PG8_LDB(B0, 0, 0); PG8_LDB(B1, 0, 1); PG8_SCHED; PG8_LDA(At, 0, 0); PG8_STAGE(PG8_SA(1, 1), a1 + hstep, voffA);
;             PG8_WAIT_V(8); PG8_WAIT_L(0); PG8_BAR; PG8_MMA(0, 0, At, B0); PG8_MMA(0, 1, At, B1); PG8_BAR; PG8_SCHED;
;             PG8_LDA(At, 0, 1); PG8_STAGE(PG8_SB(0, 0), b2, voffB); PG8_STAGE(PG8_SB(0, 1), b2 + hstep, voffB); PG8_STAGE(PG8_SA(0, 0), a2, voffA);
;             PG8_WAIT_V(8); PG8_WAIT_L(0); PG8_BAR; PG8_MMA(1, 0, At, B0); PG8_MMA(1, 1, At, B1); PG8_BAR; PG8_SCHED;
.LBB0_162:
	ds_read_b128 v[130:133], v183
	ds_read_b128 v[134:137], v183 offset:1024
	ds_read_b128 v[138:141], v183 offset:2048
	ds_read_b128 v[142:145], v183 offset:3072
	ds_read_b128 v[172:175], v184
	ds_read_b128 v[176:179], v184 offset:1024
	ds_read_b128 v[192:195], v184 offset:2048
	ds_read_b128 v[196:199], v184 offset:3072
	s_add_u32 s50, s48, 0xfffc0080
	s_addc_u32 s51, s49, -1
	s_cmp_eq_u32 s93, 12
	s_cselect_b32 s65, s5, s51
	s_cselect_b32 s64, s34, s50
	s_cselect_b32 s51, s27, s92
	s_cselect_b32 s50, s35, s41
	s_add_i32 m0, s47, 0xc000
	ds_read_b128 v[200:203], v185
	ds_read_b128 v[204:207], v185 offset:1024
	ds_read_b128 v[208:211], v185 offset:2048
	ds_read_b128 v[212:215], v185 offset:3072
	ds_read_b128 v[216:219], v185 offset:4096
	ds_read_b128 v[220:223], v185 offset:5120
	ds_read_b128 v[224:227], v185 offset:6144
	ds_read_b128 v[228:231], v185 offset:7168
	global_load_lds_dwordx4 v164, s[48:49]
	s_add_i32 m0, s47, 0xe000
	s_nop 0
	global_load_lds_dwordx4 v166, s[48:49]
	s_waitcnt vmcnt(8)
	s_waitcnt lgkmcnt(0)
	s_barrier
	s_waitcnt lgkmcnt(0)
	v_mfma_f32_16x16x32_bf16 v[126:129], v[130:133], v[200:203], v[126:129]
	v_mfma_f32_16x16x32_bf16 v[122:125], v[138:141], v[200:203], v[122:125]
	v_mfma_f32_16x16x32_bf16 v[110:113], v[130:133], v[208:211], v[110:113]
	v_mfma_f32_16x16x32_bf16 v[106:109], v[138:141], v[208:211], v[106:109]
	v_mfma_f32_16x16x32_bf16 v[94:97], v[130:133], v[216:219], v[94:97]
	v_mfma_f32_16x16x32_bf16 v[90:93], v[138:141], v[216:219], v[90:93]
	v_mfma_f32_16x16x32_bf16 v[78:81], v[130:133], v[224:227], v[78:81]
	v_mfma_f32_16x16x32_bf16 v[74:77], v[138:141], v[224:227], v[74:77]
	v_mfma_f32_16x16x32_bf16 v[126:129], v[134:137], v[204:207], v[126:129]
	v_mfma_f32_16x16x32_bf16 v[122:125], v[142:145], v[204:207], v[122:125]
	v_mfma_f32_16x16x32_bf16 v[110:113], v[134:137], v[212:215], v[110:113]
	v_mfma_f32_16x16x32_bf16 v[106:109], v[142:145], v[212:215], v[106:109]
	v_mfma_f32_16x16x32_bf16 v[94:97], v[134:137], v[220:223], v[94:97]
	v_mfma_f32_16x16x32_bf16 v[90:93], v[142:145], v[220:223], v[90:93]
	v_mfma_f32_16x16x32_bf16 v[78:81], v[134:137], v[228:231], v[78:81]
	v_mfma_f32_16x16x32_bf16 v[74:77], v[142:145], v[228:231], v[74:77]
	v_mfma_f32_16x16x32_bf16 v[118:121], v[172:175], v[200:203], v[118:121]
	v_mfma_f32_16x16x32_bf16 v[114:117], v[192:195], v[200:203], v[114:117]
	v_mfma_f32_16x16x32_bf16 v[102:105], v[172:175], v[208:211], v[102:105]
	v_mfma_f32_16x16x32_bf16 v[98:101], v[192:195], v[208:211], v[98:101]
	v_mfma_f32_16x16x32_bf16 v[86:89], v[172:175], v[216:219], v[86:89]
	v_mfma_f32_16x16x32_bf16 v[82:85], v[192:195], v[216:219], v[82:85]
	v_mfma_f32_16x16x32_bf16 v[70:73], v[172:175], v[224:227], v[70:73]
	v_mfma_f32_16x16x32_bf16 v[66:69], v[192:195], v[224:227], v[66:69]
	v_mfma_f32_16x16x32_bf16 v[118:121], v[176:179], v[204:207], v[118:121]
	v_mfma_f32_16x16x32_bf16 v[114:117], v[196:199], v[204:207], v[114:117]
	v_mfma_f32_16x16x32_bf16 v[102:105], v[176:179], v[212:215], v[102:105]
	v_mfma_f32_16x16x32_bf16 v[98:101], v[196:199], v[212:215], v[98:101]
	v_mfma_f32_16x16x32_bf16 v[86:89], v[176:179], v[220:223], v[86:89]
	v_mfma_f32_16x16x32_bf16 v[82:85], v[196:199], v[220:223], v[82:85]
	v_mfma_f32_16x16x32_bf16 v[70:73], v[176:179], v[228:231], v[70:73]
	v_mfma_f32_16x16x32_bf16 v[66:69], v[196:199], v[228:231], v[66:69]
	s_barrier
	s_add_i32 s94, s85, s72
	s_mov_b32 m0, s94
	ds_read_b128 v[200:203], v185 offset:16384
	ds_read_b128 v[204:207], v185 offset:17408
	ds_read_b128 v[208:211], v185 offset:18432
	ds_read_b128 v[212:215], v185 offset:19456
	ds_read_b128 v[216:219], v185 offset:20480
	ds_read_b128 v[220:223], v185 offset:21504
	ds_read_b128 v[224:227], v185 offset:22528
	ds_read_b128 v[228:231], v185 offset:23552
	global_load_lds_dwordx4 v148, s[50:51]
	s_add_i32 m0, s94, 0x2000
	s_add_u32 s94, s50, 0x40000
	s_addc_u32 s95, s51, 0
	s_add_i32 s96, s86, s72
	global_load_lds_dwordx4 v152, s[50:51]
	s_mov_b32 m0, s96
	s_nop 0
	global_load_lds_dwordx4 v148, s[94:95]
	s_add_i32 m0, s96, 0x2000
	s_nop 0
	global_load_lds_dwordx4 v152, s[94:95]
	s_mov_b32 m0, s47
	s_nop 0
	global_load_lds_dwordx4 v146, s[64:65]
	s_mov_b32 m0, s73
	s_nop 0
	global_load_lds_dwordx4 v150, s[64:65]
	s_waitcnt vmcnt(8)
	s_waitcnt lgkmcnt(0)
	s_barrier
	s_waitcnt lgkmcnt(0)
	v_mfma_f32_16x16x32_bf16 v[62:65], v[130:133], v[200:203], v[62:65]
	v_mfma_f32_16x16x32_bf16 v[58:61], v[138:141], v[200:203], v[58:61]
	v_mfma_f32_16x16x32_bf16 v[46:49], v[130:133], v[208:211], v[46:49]
	v_mfma_f32_16x16x32_bf16 v[42:45], v[138:141], v[208:211], v[42:45]
	v_mfma_f32_16x16x32_bf16 v[30:33], v[130:133], v[216:219], v[30:33]
	v_mfma_f32_16x16x32_bf16 v[26:29], v[138:141], v[216:219], v[26:29]
	v_mfma_f32_16x16x32_bf16 v[14:17], v[130:133], v[224:227], v[14:17]
	v_mfma_f32_16x16x32_bf16 v[10:13], v[138:141], v[224:227], v[10:13]
	v_mfma_f32_16x16x32_bf16 v[62:65], v[134:137], v[204:207], v[62:65]
	v_mfma_f32_16x16x32_bf16 v[58:61], v[142:145], v[204:207], v[58:61]
	v_mfma_f32_16x16x32_bf16 v[46:49], v[134:137], v[212:215], v[46:49]
	v_mfma_f32_16x16x32_bf16 v[42:45], v[142:145], v[212:215], v[42:45]
	v_mfma_f32_16x16x32_bf16 v[30:33], v[134:137], v[220:223], v[30:33]
	v_mfma_f32_16x16x32_bf16 v[26:29], v[142:145], v[220:223], v[26:29]
	v_mfma_f32_16x16x32_bf16 v[14:17], v[134:137], v[228:231], v[14:17]
	v_mfma_f32_16x16x32_bf16 v[10:13], v[142:145], v[228:231], v[10:13]
	v_mfma_f32_16x16x32_bf16 v[54:57], v[172:175], v[200:203], v[54:57]
	v_mfma_f32_16x16x32_bf16 v[50:53], v[192:195], v[200:203], v[50:53]
	v_mfma_f32_16x16x32_bf16 v[38:41], v[172:175], v[208:211], v[38:41]
	v_mfma_f32_16x16x32_bf16 v[34:37], v[192:195], v[208:211], v[34:37]
	v_mfma_f32_16x16x32_bf16 v[22:25], v[172:175], v[216:219], v[22:25]
	v_mfma_f32_16x16x32_bf16 v[18:21], v[192:195], v[216:219], v[18:21]
	v_mfma_f32_16x16x32_bf16 v[6:9], v[172:175], v[224:227], v[6:9]
	v_mfma_f32_16x16x32_bf16 v[2:5], v[192:195], v[224:227], v[2:5]
	v_mfma_f32_16x16x32_bf16 v[54:57], v[176:179], v[204:207], v[54:57]
	v_mfma_f32_16x16x32_bf16 v[50:53], v[196:199], v[204:207], v[50:53]
	v_mfma_f32_16x16x32_bf16 v[38:41], v[176:179], v[212:215], v[38:41]
	v_mfma_f32_16x16x32_bf16 v[34:37], v[196:199], v[212:215], v[34:37]
	v_mfma_f32_16x16x32_bf16 v[22:25], v[176:179], v[220:223], v[22:25]
	v_mfma_f32_16x16x32_bf16 v[18:21], v[196:199], v[220:223], v[18:21]
	v_mfma_f32_16x16x32_bf16 v[6:9], v[176:179], v[228:231], v[6:9]
	v_mfma_f32_16x16x32_bf16 v[2:5], v[196:199], v[228:231], v[2:5]
	s_barrier
; #define PG8_STAGE(bufoff, gbase, voff) do { _Pragma("unroll") for (int _i = 0; _i < 2; ++_i) \
;         __builtin_amdgcn_global_load_lds((const unsigned*)((const char*)(gbase) + (voff)[_i]), (PG8_LAS unsigned*)(lds + (bufoff) + ldsw + _i * 8192), 16, 0, 0); } while (0)
; #define PG8_LDA(dst, b, h) do { _Pragma("unroll") for (int m = 0; m < 4; ++m) _Pragma("unroll") for (int k = 0; k < 2; ++k) dst[m][k] = *(const PG8_LAS bf16x8*)(lds + PG8_SA(b, h) + aoff + m * 2048 + k * 1024); } while (0)
; #define PG8_LDB(dst, b, h) do { _Pragma("unroll") for (int n = 0; n < 2; ++n) _Pragma("unroll") for (int k = 0; k < 2; ++k) dst[n][k] = *(const PG8_LAS bf16x8*)(lds + PG8_SB(b, h) + boff + n * 2048 + k * 1024); } while (0)
; template <class Epi, class Sched, bool ALIGN_EPI = false, bool SP2 = false>
; __device__ __forceinline__ void gemm_phase(PG8_LAS unsigned char* lds, const Gemm g, const Sched& S, const Epi& E) {
;     ...
;         for (int t = 0; t < nt; t += 2) {
;             const bool last = (t == nt - 2);
;             const char* a1 = cA + (size_t)(t + 1) * kstep;
;             const char* a2 = last ? nA : cA + (size_t)(t + 2) * kstep; const char* b2 = last ? nB : cB + (size_t)(t + 2) * kstep;
;             const char* a3 = a2 + kstep; const char* b3 = b2 + kstep;
;             if (last && has_next) S.a_ready(nxt);
;             if constexpr (SP2) {
;             PG8_LDB(B0, 0, 0); PG8_LDB(B1, 0, 1); PG8_SCHED; PG8_LDA(At, 0, 0); PG8_STAGE(PG8_SA(1, 1), a1 + hstep, voffA);
;             PG8_WAIT_V(8); PG8_WAIT_L(0); PG8_BAR; PG8_MMA(0, 0, At, B0); PG8_MMA(0, 1, At, B1); PG8_BAR; PG8_SCHED;
;             PG8_LDA(At, 0, 1); PG8_STAGE(PG8_SB(0, 0), b2, voffB); PG8_STAGE(PG8_SB(0, 1), b2 + hstep, voffB); PG8_STAGE(PG8_SA(0, 0), a2, voffA);
;             PG8_WAIT_V(8); PG8_WAIT_L(0); PG8_BAR; PG8_MMA(1, 0, At, B0); PG8_MMA(1, 1, At, B1); PG8_BAR; PG8_SCHED;
;             PG8_LDB(B0, 1, 0); PG8_LDB(B1, 1, 1); PG8_SCHED; PG8_LDA(At, 1, 0); PG8_STAGE(PG8_SA(0, 1), a2 + hstep, voffA);
;             PG8_WAIT_V(8); PG8_WAIT_L(0); PG8_BAR; PG8_MMA(0, 0, At, B0); PG8_MMA(0, 1, At, B1); PG8_BAR; PG8_SCHED;
;             PG8_LDA(At, 1, 1); PG8_STAGE(PG8_SB(1, 0), b3, voffB); PG8_STAGE(PG8_SB(1, 1), b3 + hstep, voffB); PG8_STAGE(PG8_SA(1, 0), a3, voffA);
;             PG8_WAIT_V(8); PG8_WAIT_L(0); PG8_BAR; PG8_MMA(1, 0, At, B0); PG8_MMA(1, 1, At, B1); PG8_BAR; PG8_SCHED;
	s_add_i32 s94, 0, 0x18000
	s_add_i32 s95, 0, 0x1c000
	v_add_u32_e32 v142, s94, v181
	v_add_u32_e32 v154, s95, v181
	ds_read_b128 v[130:133], v142
	ds_read_b128 v[134:137], v142 offset:1024
	ds_read_b128 v[138:141], v142 offset:2048
	ds_read_b128 v[142:145], v142 offset:3072
	ds_read_b128 v[172:175], v154
	ds_read_b128 v[176:179], v154 offset:1024
	ds_read_b128 v[192:195], v154 offset:2048
	ds_read_b128 v[196:199], v154 offset:3072
	s_add_u32 s64, s64, 0x40000
	s_addc_u32 s65, s65, 0
	s_mov_b32 m0, s74
	ds_read_b128 v[200:203], v185 offset:32768
	ds_read_b128 v[204:207], v185 offset:33792
	ds_read_b128 v[208:211], v185 offset:34816
	ds_read_b128 v[212:215], v185 offset:35840
	ds_read_b128 v[216:219], v185 offset:36864
	ds_read_b128 v[220:223], v185 offset:37888
	ds_read_b128 v[224:227], v185 offset:38912
	ds_read_b128 v[228:231], v185 offset:39936
	global_load_lds_dwordx4 v146, s[64:65]
	s_mov_b32 m0, s75
	s_nop 0
	global_load_lds_dwordx4 v150, s[64:65]
	s_waitcnt vmcnt(8)
	s_waitcnt lgkmcnt(0)
	s_barrier
	s_waitcnt lgkmcnt(0)
	v_mfma_f32_16x16x32_bf16 v[126:129], v[130:133], v[200:203], v[126:129]
	v_mfma_f32_16x16x32_bf16 v[122:125], v[138:141], v[200:203], v[122:125]
	v_mfma_f32_16x16x32_bf16 v[110:113], v[130:133], v[208:211], v[110:113]
	v_mfma_f32_16x16x32_bf16 v[106:109], v[138:141], v[208:211], v[106:109]
	v_mfma_f32_16x16x32_bf16 v[94:97], v[130:133], v[216:219], v[94:97]
	v_mfma_f32_16x16x32_bf16 v[90:93], v[138:141], v[216:219], v[90:93]
	v_mfma_f32_16x16x32_bf16 v[78:81], v[130:133], v[224:227], v[78:81]
	v_mfma_f32_16x16x32_bf16 v[74:77], v[138:141], v[224:227], v[74:77]
	v_mfma_f32_16x16x32_bf16 v[126:129], v[134:137], v[204:207], v[126:129]
	v_mfma_f32_16x16x32_bf16 v[122:125], v[142:145], v[204:207], v[122:125]
	v_mfma_f32_16x16x32_bf16 v[110:113], v[134:137], v[212:215], v[110:113]
	v_mfma_f32_16x16x32_bf16 v[106:109], v[142:145], v[212:215], v[106:109]
	v_mfma_f32_16x16x32_bf16 v[94:97], v[134:137], v[220:223], v[94:97]
	v_mfma_f32_16x16x32_bf16 v[90:93], v[142:145], v[220:223], v[90:93]
	v_mfma_f32_16x16x32_bf16 v[78:81], v[134:137], v[228:231], v[78:81]
	v_mfma_f32_16x16x32_bf16 v[74:77], v[142:145], v[228:231], v[74:77]
	v_mfma_f32_16x16x32_bf16 v[118:121], v[172:175], v[200:203], v[118:121]
	v_mfma_f32_16x16x32_bf16 v[114:117], v[192:195], v[200:203], v[114:117]
	v_mfma_f32_16x16x32_bf16 v[102:105], v[172:175], v[208:211], v[102:105]
	v_mfma_f32_16x16x32_bf16 v[98:101], v[192:195], v[208:211], v[98:101]
	v_mfma_f32_16x16x32_bf16 v[86:89], v[172:175], v[216:219], v[86:89]
	v_mfma_f32_16x16x32_bf16 v[82:85], v[192:195], v[216:219], v[82:85]
	v_mfma_f32_16x16x32_bf16 v[70:73], v[172:175], v[224:227], v[70:73]
	v_mfma_f32_16x16x32_bf16 v[66:69], v[192:195], v[224:227], v[66:69]
	v_mfma_f32_16x16x32_bf16 v[118:121], v[176:179], v[204:207], v[118:121]
	v_mfma_f32_16x16x32_bf16 v[114:117], v[196:199], v[204:207], v[114:117]
	v_mfma_f32_16x16x32_bf16 v[102:105], v[176:179], v[212:215], v[102:105]
	v_mfma_f32_16x16x32_bf16 v[98:101], v[196:199], v[212:215], v[98:101]
	v_mfma_f32_16x16x32_bf16 v[86:89], v[176:179], v[220:223], v[86:89]
	v_mfma_f32_16x16x32_bf16 v[82:85], v[196:199], v[220:223], v[82:85]
	v_mfma_f32_16x16x32_bf16 v[70:73], v[176:179], v[228:231], v[70:73]
	v_mfma_f32_16x16x32_bf16 v[66:69], v[196:199], v[228:231], v[66:69]
	s_barrier
	s_add_i32 s96, s94, s72
	s_add_u32 s12, s50, 0x80
	s_addc_u32 s13, s51, 0
	s_mov_b32 m0, s96
	ds_read_b128 v[200:203], v185 offset:49152
	ds_read_b128 v[204:207], v185 offset:50176
	ds_read_b128 v[208:211], v185 offset:51200
	ds_read_b128 v[212:215], v185 offset:52224
	ds_read_b128 v[216:219], v185 offset:53248
	ds_read_b128 v[220:223], v185 offset:54272
	ds_read_b128 v[224:227], v185 offset:55296
	ds_read_b128 v[228:231], v185 offset:56320
	global_load_lds_dwordx4 v148, s[12:13]
	s_add_i32 m0, s96, 0x2000
	s_add_u32 s50, s50, 0x40080
	s_addc_u32 s51, s51, 0
	s_add_i32 s96, s95, s72
	global_load_lds_dwordx4 v152, s[12:13]
	s_mov_b32 m0, s96
	s_nop 0
	global_load_lds_dwordx4 v148, s[50:51]
	s_add_i32 m0, s96, 0x2000
	s_nop 0
	global_load_lds_dwordx4 v152, s[50:51]
	s_add_u32 s64, s64, 0xfffc0080
	s_addc_u32 s65, s65, -1
	s_mov_b32 m0, s82
	s_nop 0
	global_load_lds_dwordx4 v146, s[64:65]
	s_mov_b32 m0, s83
	s_nop 0
	global_load_lds_dwordx4 v150, s[64:65]
	s_waitcnt vmcnt(8)
	s_waitcnt lgkmcnt(0)
	s_barrier
	s_waitcnt lgkmcnt(0)
	v_mfma_f32_16x16x32_bf16 v[62:65], v[130:133], v[200:203], v[62:65]
	v_mfma_f32_16x16x32_bf16 v[58:61], v[138:141], v[200:203], v[58:61]
	v_mfma_f32_16x16x32_bf16 v[46:49], v[130:133], v[208:211], v[46:49]
	v_mfma_f32_16x16x32_bf16 v[42:45], v[138:141], v[208:211], v[42:45]
	v_mfma_f32_16x16x32_bf16 v[30:33], v[130:133], v[216:219], v[30:33]
	v_mfma_f32_16x16x32_bf16 v[26:29], v[138:141], v[216:219], v[26:29]
	v_mfma_f32_16x16x32_bf16 v[14:17], v[130:133], v[224:227], v[14:17]
	v_mfma_f32_16x16x32_bf16 v[10:13], v[138:141], v[224:227], v[10:13]
	v_mfma_f32_16x16x32_bf16 v[62:65], v[134:137], v[204:207], v[62:65]
	v_mfma_f32_16x16x32_bf16 v[58:61], v[142:145], v[204:207], v[58:61]
	v_mfma_f32_16x16x32_bf16 v[46:49], v[134:137], v[212:215], v[46:49]
	v_mfma_f32_16x16x32_bf16 v[42:45], v[142:145], v[212:215], v[42:45]
	v_mfma_f32_16x16x32_bf16 v[30:33], v[134:137], v[220:223], v[30:33]
	v_mfma_f32_16x16x32_bf16 v[26:29], v[142:145], v[220:223], v[26:29]
	v_mfma_f32_16x16x32_bf16 v[14:17], v[134:137], v[228:231], v[14:17]
	v_mfma_f32_16x16x32_bf16 v[10:13], v[142:145], v[228:231], v[10:13]
	v_mfma_f32_16x16x32_bf16 v[54:57], v[172:175], v[200:203], v[54:57]
	v_mfma_f32_16x16x32_bf16 v[50:53], v[192:195], v[200:203], v[50:53]
	v_mfma_f32_16x16x32_bf16 v[38:41], v[172:175], v[208:211], v[38:41]
	v_mfma_f32_16x16x32_bf16 v[34:37], v[192:195], v[208:211], v[34:37]
	v_mfma_f32_16x16x32_bf16 v[22:25], v[172:175], v[216:219], v[22:25]
	v_mfma_f32_16x16x32_bf16 v[18:21], v[192:195], v[216:219], v[18:21]
	v_mfma_f32_16x16x32_bf16 v[6:9], v[172:175], v[224:227], v[6:9]
	v_mfma_f32_16x16x32_bf16 v[2:5], v[192:195], v[224:227], v[2:5]
	v_mfma_f32_16x16x32_bf16 v[54:57], v[176:179], v[204:207], v[54:57]
	v_mfma_f32_16x16x32_bf16 v[50:53], v[196:199], v[204:207], v[50:53]
	v_mfma_f32_16x16x32_bf16 v[38:41], v[176:179], v[212:215], v[38:41]
	v_mfma_f32_16x16x32_bf16 v[34:37], v[196:199], v[212:215], v[34:37]
	v_mfma_f32_16x16x32_bf16 v[22:25], v[176:179], v[220:223], v[22:25]
	v_mfma_f32_16x16x32_bf16 v[18:21], v[196:199], v[220:223], v[18:21]
	v_mfma_f32_16x16x32_bf16 v[6:9], v[176:179], v[228:231], v[6:9]
	v_mfma_f32_16x16x32_bf16 v[2:5], v[196:199], v[228:231], v[2:5]
	s_add_i32 s93, s93, 2
	s_add_u32 s48, s48, 0x100
	s_addc_u32 s49, s49, 0
	s_add_u32 s41, s41, 0x100
	s_addc_u32 s92, s92, 0
	s_cmp_gt_u32 s93, 13
	s_cbranch_scc1 .Lp1_kexit
	s_barrier
	s_branch .LBB0_162

; #define PG8_STAGE(bufoff, gbase, voff) do { _Pragma("unroll") for (int _i = 0; _i < 2; ++_i) \
;         __builtin_amdgcn_global_load_lds((const unsigned*)((const char*)(gbase) + (voff)[_i]), (PG8_LAS unsigned*)(lds + (bufoff) + ldsw + _i * 8192), 16, 0, 0); } while (0)
; #define PG8_LDA(dst, b, h) do { _Pragma("unroll") for (int m = 0; m < 4; ++m) _Pragma("unroll") for (int k = 0; k < 2; ++k) dst[m][k] = *(const PG8_LAS bf16x8*)(lds + PG8_SA(b, h) + aoff + m * 2048 + k * 1024); } while (0)
; #define PG8_LDB(dst, b, h) do { _Pragma("unroll") for (int n = 0; n < 2; ++n) _Pragma("unroll") for (int k = 0; k < 2; ++k) dst[n][k] = *(const PG8_LAS bf16x8*)(lds + PG8_SB(b, h) + boff + n * 2048 + k * 1024); } while (0)
; #define PG8_MMA(ai, bj, At, Bt) do { __builtin_amdgcn_s_setprio(1); _Pragma("unroll") for (int m = 0; m < 4; ++m) _Pragma("unroll") for (int n = 0; n < 2; ++n) _Pragma("unroll") for (int k = 0; k < 2; ++k) \
;         acc[ai][bj][m][n] = __builtin_amdgcn_mfma_f32_16x16x32_bf16(Bt[n][k], At[m][k], acc[ai][bj][m][n], 0, 0, 0); __builtin_amdgcn_s_setprio(0); } while (0)
; #define PG8_WAIT_V(n) asm volatile("s_waitcnt vmcnt(" #n ")" ::: "memory")
; #define PG8_WAIT_L(n) asm volatile("s_waitcnt lgkmcnt(" #n ")" ::: "memory")
; #define PG8_BAR __builtin_amdgcn_s_barrier()
; #define PG8_SCHED __builtin_amdgcn_sched_barrier(0)
; template <class Epi, class Sched, bool ALIGN_EPI = false, bool SP2 = false>
; __device__ __forceinline__ void gemm_phase(PG8_LAS unsigned char* lds, const Gemm g, const Sched& S, const Epi& E) {
;     ...
;             PG8_LDB(B0, 0, 0); PG8_LDB(B1, 0, 1); PG8_SCHED; PG8_LDA(At, 0, 0); PG8_STAGE(PG8_SA(1, 1), a1 + hstep, voffA);
;             PG8_WAIT_V(8); PG8_WAIT_L(0); PG8_BAR; PG8_MMA(0, 0, At, B0); PG8_MMA(0, 1, At, B1); PG8_BAR; PG8_SCHED;
;             PG8_LDA(At, 0, 1); PG8_STAGE(PG8_SB(0, 0), b2, voffB); PG8_STAGE(PG8_SB(0, 1), b2 + hstep, voffB); PG8_STAGE(PG8_SA(0, 0), a2, voffA);
;             PG8_WAIT_V(8); PG8_WAIT_L(0); PG8_BAR; PG8_MMA(1, 0, At, B0); PG8_MMA(1, 1, At, B1); PG8_BAR; PG8_SCHED;
.Lp1_peel:
	ds_read_b128 v[130:133], v183
	ds_read_b128 v[134:137], v183 offset:1024
	ds_read_b128 v[138:141], v183 offset:2048
	ds_read_b128 v[142:145], v183 offset:3072
	ds_read_b128 v[172:175], v184
	ds_read_b128 v[176:179], v184 offset:1024
	ds_read_b128 v[192:195], v184 offset:2048
	ds_read_b128 v[196:199], v184 offset:3072
	s_add_u32 s50, s48, 0xfffc0080
	s_addc_u32 s51, s49, -1
	s_cmp_eq_u32 s93, 12
	s_cselect_b32 s65, s5, s51
	s_cselect_b32 s64, s34, s50
	s_cselect_b32 s51, s27, s92
	s_cselect_b32 s50, s35, s41
	ds_read_b128 v[200:203], v185
	ds_read_b128 v[204:207], v185 offset:1024
	ds_read_b128 v[208:211], v185 offset:2048
	ds_read_b128 v[212:215], v185 offset:3072
	ds_read_b128 v[216:219], v185 offset:4096
	ds_read_b128 v[220:223], v185 offset:5120
	ds_read_b128 v[224:227], v185 offset:6144
	ds_read_b128 v[228:231], v185 offset:7168
	s_waitcnt vmcnt(24)
	s_waitcnt lgkmcnt(0)
	s_barrier
	s_waitcnt lgkmcnt(0)
	v_mfma_f32_16x16x32_bf16 v[126:129], v[130:133], v[200:203], 0
	v_mfma_f32_16x16x32_bf16 v[122:125], v[138:141], v[200:203], 0
	v_mfma_f32_16x16x32_bf16 v[110:113], v[130:133], v[208:211], 0
	v_mfma_f32_16x16x32_bf16 v[106:109], v[138:141], v[208:211], 0
	v_mfma_f32_16x16x32_bf16 v[94:97], v[130:133], v[216:219], 0
	v_mfma_f32_16x16x32_bf16 v[90:93], v[138:141], v[216:219], 0
	v_mfma_f32_16x16x32_bf16 v[78:81], v[130:133], v[224:227], 0
	v_mfma_f32_16x16x32_bf16 v[74:77], v[138:141], v[224:227], 0
	v_mfma_f32_16x16x32_bf16 v[126:129], v[134:137], v[204:207], v[126:129]
	v_mfma_f32_16x16x32_bf16 v[122:125], v[142:145], v[204:207], v[122:125]
	v_mfma_f32_16x16x32_bf16 v[110:113], v[134:137], v[212:215], v[110:113]
	v_mfma_f32_16x16x32_bf16 v[106:109], v[142:145], v[212:215], v[106:109]
	v_mfma_f32_16x16x32_bf16 v[94:97], v[134:137], v[220:223], v[94:97]
	v_mfma_f32_16x16x32_bf16 v[90:93], v[142:145], v[220:223], v[90:93]
	v_mfma_f32_16x16x32_bf16 v[78:81], v[134:137], v[228:231], v[78:81]
	v_mfma_f32_16x16x32_bf16 v[74:77], v[142:145], v[228:231], v[74:77]
	v_mfma_f32_16x16x32_bf16 v[118:121], v[172:175], v[200:203], 0
	v_mfma_f32_16x16x32_bf16 v[114:117], v[192:195], v[200:203], 0
	v_mfma_f32_16x16x32_bf16 v[102:105], v[172:175], v[208:211], 0
	v_mfma_f32_16x16x32_bf16 v[98:101], v[192:195], v[208:211], 0
	v_mfma_f32_16x16x32_bf16 v[86:89], v[172:175], v[216:219], 0
	v_mfma_f32_16x16x32_bf16 v[82:85], v[192:195], v[216:219], 0
	v_mfma_f32_16x16x32_bf16 v[70:73], v[172:175], v[224:227], 0
	v_mfma_f32_16x16x32_bf16 v[66:69], v[192:195], v[224:227], 0
	v_mfma_f32_16x16x32_bf16 v[118:121], v[176:179], v[204:207], v[118:121]
	v_mfma_f32_16x16x32_bf16 v[114:117], v[196:199], v[204:207], v[114:117]
	v_mfma_f32_16x16x32_bf16 v[102:105], v[176:179], v[212:215], v[102:105]
	v_mfma_f32_16x16x32_bf16 v[98:101], v[196:199], v[212:215], v[98:101]
	v_mfma_f32_16x16x32_bf16 v[86:89], v[176:179], v[220:223], v[86:89]
	v_mfma_f32_16x16x32_bf16 v[82:85], v[196:199], v[220:223], v[82:85]
	v_mfma_f32_16x16x32_bf16 v[70:73], v[176:179], v[228:231], v[70:73]
	v_mfma_f32_16x16x32_bf16 v[66:69], v[196:199], v[228:231], v[66:69]
	s_barrier
	s_add_i32 s94, s85, s72
	s_mov_b32 m0, s94
	ds_read_b128 v[200:203], v185 offset:16384
	ds_read_b128 v[204:207], v185 offset:17408
	ds_read_b128 v[208:211], v185 offset:18432
	ds_read_b128 v[212:215], v185 offset:19456
	ds_read_b128 v[216:219], v185 offset:20480
	ds_read_b128 v[220:223], v185 offset:21504
	ds_read_b128 v[224:227], v185 offset:22528
	ds_read_b128 v[228:231], v185 offset:23552
	global_load_lds_dwordx4 v148, s[50:51]
	s_add_i32 m0, s94, 0x2000
	s_add_u32 s94, s50, 0x40000
	s_addc_u32 s95, s51, 0
	s_add_i32 s96, s86, s72
	global_load_lds_dwordx4 v152, s[50:51]
	s_mov_b32 m0, s96
	s_nop 0
	global_load_lds_dwordx4 v148, s[94:95]
	s_add_i32 m0, s96, 0x2000
	s_nop 0
	global_load_lds_dwordx4 v152, s[94:95]
	s_mov_b32 m0, s47
	s_nop 0
	global_load_lds_dwordx4 v146, s[64:65]
	s_mov_b32 m0, s73
	s_nop 0
	global_load_lds_dwordx4 v150, s[64:65]
	s_waitcnt vmcnt(24)
	s_waitcnt lgkmcnt(0)
	s_barrier
	s_waitcnt lgkmcnt(0)
	v_mfma_f32_16x16x32_bf16 v[62:65], v[130:133], v[200:203], 0
	v_mfma_f32_16x16x32_bf16 v[58:61], v[138:141], v[200:203], 0
	v_mfma_f32_16x16x32_bf16 v[46:49], v[130:133], v[208:211], 0
	v_mfma_f32_16x16x32_bf16 v[42:45], v[138:141], v[208:211], 0
	v_mfma_f32_16x16x32_bf16 v[30:33], v[130:133], v[216:219], 0
	v_mfma_f32_16x16x32_bf16 v[26:29], v[138:141], v[216:219], 0
	v_mfma_f32_16x16x32_bf16 v[14:17], v[130:133], v[224:227], 0
	v_mfma_f32_16x16x32_bf16 v[10:13], v[138:141], v[224:227], 0
	v_mfma_f32_16x16x32_bf16 v[62:65], v[134:137], v[204:207], v[62:65]
	v_mfma_f32_16x16x32_bf16 v[58:61], v[142:145], v[204:207], v[58:61]
	v_mfma_f32_16x16x32_bf16 v[46:49], v[134:137], v[212:215], v[46:49]
	v_mfma_f32_16x16x32_bf16 v[42:45], v[142:145], v[212:215], v[42:45]
	v_mfma_f32_16x16x32_bf16 v[30:33], v[134:137], v[220:223], v[30:33]
	v_mfma_f32_16x16x32_bf16 v[26:29], v[142:145], v[220:223], v[26:29]
	v_mfma_f32_16x16x32_bf16 v[14:17], v[134:137], v[228:231], v[14:17]
	v_mfma_f32_16x16x32_bf16 v[10:13], v[142:145], v[228:231], v[10:13]
	v_mfma_f32_16x16x32_bf16 v[54:57], v[172:175], v[200:203], 0
	v_mfma_f32_16x16x32_bf16 v[50:53], v[192:195], v[200:203], 0
	v_mfma_f32_16x16x32_bf16 v[38:41], v[172:175], v[208:211], 0
	v_mfma_f32_16x16x32_bf16 v[34:37], v[192:195], v[208:211], 0
	v_mfma_f32_16x16x32_bf16 v[22:25], v[172:175], v[216:219], 0
	v_mfma_f32_16x16x32_bf16 v[18:21], v[192:195], v[216:219], 0
	v_mfma_f32_16x16x32_bf16 v[6:9], v[172:175], v[224:227], 0
	v_mfma_f32_16x16x32_bf16 v[2:5], v[192:195], v[224:227], 0
	v_mfma_f32_16x16x32_bf16 v[54:57], v[176:179], v[204:207], v[54:57]
	v_mfma_f32_16x16x32_bf16 v[50:53], v[196:199], v[204:207], v[50:53]
	v_mfma_f32_16x16x32_bf16 v[38:41], v[176:179], v[212:215], v[38:41]
	v_mfma_f32_16x16x32_bf16 v[34:37], v[196:199], v[212:215], v[34:37]
	v_mfma_f32_16x16x32_bf16 v[22:25], v[176:179], v[220:223], v[22:25]
	v_mfma_f32_16x16x32_bf16 v[18:21], v[196:199], v[220:223], v[18:21]
	v_mfma_f32_16x16x32_bf16 v[6:9], v[176:179], v[228:231], v[6:9]
	v_mfma_f32_16x16x32_bf16 v[2:5], v[196:199], v[228:231], v[2:5]
	s_barrier
; #define PG8_STAGE(bufoff, gbase, voff) do { _Pragma("unroll") for (int _i = 0; _i < 2; ++_i) \
;         __builtin_amdgcn_global_load_lds((const unsigned*)((const char*)(gbase) + (voff)[_i]), (PG8_LAS unsigned*)(lds + (bufoff) + ldsw + _i * 8192), 16, 0, 0); } while (0)
; #define PG8_LDA(dst, b, h) do { _Pragma("unroll") for (int m = 0; m < 4; ++m) _Pragma("unroll") for (int k = 0; k < 2; ++k) dst[m][k] = *(const PG8_LAS bf16x8*)(lds + PG8_SA(b, h) + aoff + m * 2048 + k * 1024); } while (0)
; #define PG8_LDB(dst, b, h) do { _Pragma("unroll") for (int n = 0; n < 2; ++n) _Pragma("unroll") for (int k = 0; k < 2; ++k) dst[n][k] = *(const PG8_LAS bf16x8*)(lds + PG8_SB(b, h) + boff + n * 2048 + k * 1024); } while (0)
; #define PG8_MMA(ai, bj, At, Bt) do { __builtin_amdgcn_s_setprio(1); _Pragma("unroll") for (int m = 0; m < 4; ++m) _Pragma("unroll") for (int n = 0; n < 2; ++n) _Pragma("unroll") for (int k = 0; k < 2; ++k) \
;         acc[ai][bj][m][n] = __builtin_amdgcn_mfma_f32_16x16x32_bf16(Bt[n][k], At[m][k], acc[ai][bj][m][n], 0, 0, 0); __builtin_amdgcn_s_setprio(0); } while (0)
; #define PG8_WAIT_V(n) asm volatile("s_waitcnt vmcnt(" #n ")" ::: "memory")
; #define PG8_WAIT_L(n) asm volatile("s_waitcnt lgkmcnt(" #n ")" ::: "memory")
; #define PG8_BAR __builtin_amdgcn_s_barrier()
; #define PG8_SCHED __builtin_amdgcn_sched_barrier(0)
; template <class Epi, class Sched, bool ALIGN_EPI = false, bool SP2 = false>
; __device__ __forceinline__ void gemm_phase(PG8_LAS unsigned char* lds, const Gemm g, const Sched& S, const Epi& E) {
;     ...
;             PG8_LDB(B0, 1, 0); PG8_LDB(B1, 1, 1); PG8_SCHED; PG8_LDA(At, 1, 0); PG8_STAGE(PG8_SA(0, 1), a2 + hstep, voffA);
;             PG8_WAIT_V(8); PG8_WAIT_L(0); PG8_BAR; PG8_MMA(0, 0, At, B0); PG8_MMA(0, 1, At, B1); PG8_BAR; PG8_SCHED;
;             PG8_LDA(At, 1, 1); PG8_STAGE(PG8_SB(1, 0), b3, voffB); PG8_STAGE(PG8_SB(1, 1), b3 + hstep, voffB); PG8_STAGE(PG8_SA(1, 0), a3, voffA);
;             PG8_WAIT_V(8); PG8_WAIT_L(0); PG8_BAR; PG8_MMA(1, 0, At, B0); PG8_MMA(1, 1, At, B1); PG8_BAR; PG8_SCHED;
;     ...
;     PG8_WAIT_V(0);
;     if constexpr (!ALIGN_EPI) { if (wr == 0) PG8_BAR; }
;     PG8_BAR;
	s_add_i32 s94, 0, 0x18000
	s_add_i32 s95, 0, 0x1c000
	v_add_u32_e32 v142, s94, v181
	v_add_u32_e32 v154, s95, v181
	ds_read_b128 v[130:133], v142
	ds_read_b128 v[134:137], v142 offset:1024
	ds_read_b128 v[138:141], v142 offset:2048
	ds_read_b128 v[142:145], v142 offset:3072
	ds_read_b128 v[172:175], v154
	ds_read_b128 v[176:179], v154 offset:1024
	ds_read_b128 v[192:195], v154 offset:2048
	ds_read_b128 v[196:199], v154 offset:3072
	s_add_u32 s64, s64, 0x40000
	s_addc_u32 s65, s65, 0
	s_mov_b32 m0, s74
	ds_read_b128 v[200:203], v185 offset:32768
	ds_read_b128 v[204:207], v185 offset:33792
	ds_read_b128 v[208:211], v185 offset:34816
	ds_read_b128 v[212:215], v185 offset:35840
	ds_read_b128 v[216:219], v185 offset:36864
	ds_read_b128 v[220:223], v185 offset:37888
	ds_read_b128 v[224:227], v185 offset:38912
	ds_read_b128 v[228:231], v185 offset:39936
	global_load_lds_dwordx4 v146, s[64:65]
	s_mov_b32 m0, s75
	s_nop 0
	global_load_lds_dwordx4 v150, s[64:65]
	s_waitcnt vmcnt(24)
	s_waitcnt lgkmcnt(0)
	s_barrier
	s_waitcnt lgkmcnt(0)
	v_mfma_f32_16x16x32_bf16 v[126:129], v[130:133], v[200:203], v[126:129]
	v_mfma_f32_16x16x32_bf16 v[122:125], v[138:141], v[200:203], v[122:125]
	v_mfma_f32_16x16x32_bf16 v[110:113], v[130:133], v[208:211], v[110:113]
	v_mfma_f32_16x16x32_bf16 v[106:109], v[138:141], v[208:211], v[106:109]
	v_mfma_f32_16x16x32_bf16 v[94:97], v[130:133], v[216:219], v[94:97]
	v_mfma_f32_16x16x32_bf16 v[90:93], v[138:141], v[216:219], v[90:93]
	v_mfma_f32_16x16x32_bf16 v[78:81], v[130:133], v[224:227], v[78:81]
	v_mfma_f32_16x16x32_bf16 v[74:77], v[138:141], v[224:227], v[74:77]
	v_mfma_f32_16x16x32_bf16 v[126:129], v[134:137], v[204:207], v[126:129]
	v_mfma_f32_16x16x32_bf16 v[122:125], v[142:145], v[204:207], v[122:125]
	v_mfma_f32_16x16x32_bf16 v[110:113], v[134:137], v[212:215], v[110:113]
	v_mfma_f32_16x16x32_bf16 v[106:109], v[142:145], v[212:215], v[106:109]
	v_mfma_f32_16x16x32_bf16 v[94:97], v[134:137], v[220:223], v[94:97]
	v_mfma_f32_16x16x32_bf16 v[90:93], v[142:145], v[220:223], v[90:93]
	v_mfma_f32_16x16x32_bf16 v[78:81], v[134:137], v[228:231], v[78:81]
	v_mfma_f32_16x16x32_bf16 v[74:77], v[142:145], v[228:231], v[74:77]
	v_mfma_f32_16x16x32_bf16 v[118:121], v[172:175], v[200:203], v[118:121]
	v_mfma_f32_16x16x32_bf16 v[114:117], v[192:195], v[200:203], v[114:117]
	v_mfma_f32_16x16x32_bf16 v[102:105], v[172:175], v[208:211], v[102:105]
	v_mfma_f32_16x16x32_bf16 v[98:101], v[192:195], v[208:211], v[98:101]
	v_mfma_f32_16x16x32_bf16 v[86:89], v[172:175], v[216:219], v[86:89]
	v_mfma_f32_16x16x32_bf16 v[82:85], v[192:195], v[216:219], v[82:85]
	v_mfma_f32_16x16x32_bf16 v[70:73], v[172:175], v[224:227], v[70:73]
	v_mfma_f32_16x16x32_bf16 v[66:69], v[192:195], v[224:227], v[66:69]
	v_mfma_f32_16x16x32_bf16 v[118:121], v[176:179], v[204:207], v[118:121]
	v_mfma_f32_16x16x32_bf16 v[114:117], v[196:199], v[204:207], v[114:117]
	v_mfma_f32_16x16x32_bf16 v[102:105], v[176:179], v[212:215], v[102:105]
	v_mfma_f32_16x16x32_bf16 v[98:101], v[196:199], v[212:215], v[98:101]
	v_mfma_f32_16x16x32_bf16 v[86:89], v[176:179], v[220:223], v[86:89]
	v_mfma_f32_16x16x32_bf16 v[82:85], v[196:199], v[220:223], v[82:85]
	v_mfma_f32_16x16x32_bf16 v[70:73], v[176:179], v[228:231], v[70:73]
	v_mfma_f32_16x16x32_bf16 v[66:69], v[196:199], v[228:231], v[66:69]
	s_barrier
	s_add_i32 s96, s94, s72
	s_add_u32 s12, s50, 0x80
	s_addc_u32 s13, s51, 0
	s_mov_b32 m0, s96
	ds_read_b128 v[200:203], v185 offset:49152
	ds_read_b128 v[204:207], v185 offset:50176
	ds_read_b128 v[208:211], v185 offset:51200
	ds_read_b128 v[212:215], v185 offset:52224
	ds_read_b128 v[216:219], v185 offset:53248
	ds_read_b128 v[220:223], v185 offset:54272
	ds_read_b128 v[224:227], v185 offset:55296
	ds_read_b128 v[228:231], v185 offset:56320
	global_load_lds_dwordx4 v148, s[12:13]
	s_add_i32 m0, s96, 0x2000
	s_add_u32 s50, s50, 0x40080
	s_addc_u32 s51, s51, 0
	s_add_i32 s96, s95, s72
	global_load_lds_dwordx4 v152, s[12:13]
	s_mov_b32 m0, s96
	s_nop 0
	global_load_lds_dwordx4 v148, s[50:51]
	s_add_i32 m0, s96, 0x2000
	s_nop 0
	global_load_lds_dwordx4 v152, s[50:51]
	s_add_u32 s64, s64, 0xfffc0080
	s_addc_u32 s65, s65, -1
	s_mov_b32 m0, s82
	s_nop 0
	global_load_lds_dwordx4 v146, s[64:65]
	s_mov_b32 m0, s83
	s_nop 0
	global_load_lds_dwordx4 v150, s[64:65]
	s_waitcnt vmcnt(8)
	s_waitcnt lgkmcnt(0)
	s_barrier
	s_waitcnt lgkmcnt(0)
	v_mfma_f32_16x16x32_bf16 v[62:65], v[130:133], v[200:203], v[62:65]
	v_mfma_f32_16x16x32_bf16 v[58:61], v[138:141], v[200:203], v[58:61]
	v_mfma_f32_16x16x32_bf16 v[46:49], v[130:133], v[208:211], v[46:49]
	v_mfma_f32_16x16x32_bf16 v[42:45], v[138:141], v[208:211], v[42:45]
	v_mfma_f32_16x16x32_bf16 v[30:33], v[130:133], v[216:219], v[30:33]
	v_mfma_f32_16x16x32_bf16 v[26:29], v[138:141], v[216:219], v[26:29]
	v_mfma_f32_16x16x32_bf16 v[14:17], v[130:133], v[224:227], v[14:17]
	v_mfma_f32_16x16x32_bf16 v[10:13], v[138:141], v[224:227], v[10:13]
	v_mfma_f32_16x16x32_bf16 v[62:65], v[134:137], v[204:207], v[62:65]
	v_mfma_f32_16x16x32_bf16 v[58:61], v[142:145], v[204:207], v[58:61]
	v_mfma_f32_16x16x32_bf16 v[46:49], v[134:137], v[212:215], v[46:49]
	v_mfma_f32_16x16x32_bf16 v[42:45], v[142:145], v[212:215], v[42:45]
	v_mfma_f32_16x16x32_bf16 v[30:33], v[134:137], v[220:223], v[30:33]
	v_mfma_f32_16x16x32_bf16 v[26:29], v[142:145], v[220:223], v[26:29]
	v_mfma_f32_16x16x32_bf16 v[14:17], v[134:137], v[228:231], v[14:17]
	v_mfma_f32_16x16x32_bf16 v[10:13], v[142:145], v[228:231], v[10:13]
	v_mfma_f32_16x16x32_bf16 v[54:57], v[172:175], v[200:203], v[54:57]
	v_mfma_f32_16x16x32_bf16 v[50:53], v[192:195], v[200:203], v[50:53]
	v_mfma_f32_16x16x32_bf16 v[38:41], v[172:175], v[208:211], v[38:41]
	v_mfma_f32_16x16x32_bf16 v[34:37], v[192:195], v[208:211], v[34:37]
	v_mfma_f32_16x16x32_bf16 v[22:25], v[172:175], v[216:219], v[22:25]
	v_mfma_f32_16x16x32_bf16 v[18:21], v[192:195], v[216:219], v[18:21]
	v_mfma_f32_16x16x32_bf16 v[6:9], v[172:175], v[224:227], v[6:9]
	v_mfma_f32_16x16x32_bf16 v[2:5], v[192:195], v[224:227], v[2:5]
	v_mfma_f32_16x16x32_bf16 v[54:57], v[176:179], v[204:207], v[54:57]
	v_mfma_f32_16x16x32_bf16 v[50:53], v[196:199], v[204:207], v[50:53]
	v_mfma_f32_16x16x32_bf16 v[38:41], v[176:179], v[212:215], v[38:41]
	v_mfma_f32_16x16x32_bf16 v[34:37], v[196:199], v[212:215], v[34:37]
	v_mfma_f32_16x16x32_bf16 v[22:25], v[176:179], v[220:223], v[22:25]
	v_mfma_f32_16x16x32_bf16 v[18:21], v[196:199], v[220:223], v[18:21]
	v_mfma_f32_16x16x32_bf16 v[6:9], v[176:179], v[228:231], v[6:9]
	v_mfma_f32_16x16x32_bf16 v[2:5], v[196:199], v[228:231], v[2:5]
	s_barrier
	s_add_i32 s93, s93, 2
	s_add_u32 s48, s48, 0x100
	s_addc_u32 s49, s49, 0
	s_add_u32 s41, s41, 0x100
	s_addc_u32 s92, s92, 0
	s_branch .LBB0_162
.LBB0_208:
	s_setprio 0
	s_waitcnt vmcnt(0)
	v_readlane_b32 s78, v250, 0
	v_readlane_b32 s79, v250, 1
	s_barrier

; #define PG8_STAGE(bufoff, gbase, voff) do { _Pragma("unroll") for (int _i = 0; _i < 2; ++_i) \
;         __builtin_amdgcn_global_load_lds((const unsigned*)((const char*)(gbase) + (voff)[_i]), (PG8_LAS unsigned*)(lds + (bufoff) + ldsw + _i * 8192), 16, 0, 0); } while (0)
; #define PG8_WAIT_V(n) asm volatile("s_waitcnt vmcnt(" #n ")" ::: "memory")
; #define PG8_BAR __builtin_amdgcn_s_barrier()
; template <class Epi, class Sched, bool ALIGN_EPI = false, bool SP2 = false>
; __device__ __forceinline__ void gemm_phase(PG8_LAS unsigned char* lds, const Gemm g, const Sched& S, const Epi& E) {
;     ...
;         PG8_STAGE(PG8_SB(1, 0), cB + kstep, voffB); PG8_STAGE(PG8_SA(1, 0), cA + kstep, voffA); PG8_STAGE(PG8_SB(1, 1), cB + hstep + kstep, voffB);
;         PG8_WAIT_V(6); PG8_BAR;
;     __device__ __forceinline__ void operator()(const f32x4 (&acc)[2][2][4][2], const pg8::Unit& u, int wr, int wc, int fr, int fq) const {
;         const int row0 = u.pm * 256 + wr * 64 + fr, col0 = u.pn * 256 + wc * 32 + 8 * fq;
;         const int s = (u.pm * 256 < NP) ? ((u.pm * 256) >> 12) : 16;
;         const float* gate = mod + s * 3072 + 2048;
;         f32x4 gv[2][2];
; #pragma unroll
;         for (int bj = 0; bj < 2; ++bj)
; #pragma unroll
;             for (int n = 0; n < 2; ++n) gv[bj][n] = *(const f32x4*)(gate + col0 + 128 * bj + 4 * n);
;         const float* xbase = (u.pm * 256 < NP) ? xp : xs - (size_t)NP * DM;
.LBB0_451:
	s_ashr_i32 s53, s3, 31
	s_add_u32 s54, s38, 0xf0000000
	s_addc_u32 s55, s39, -1
	s_lshl_b32 s6, s6, 5
	s_and_b32 s12, s6, 0x60
	s_mov_b64 s[6:7], 0x80
	s_add_i32 m0, s31, 0x18000
	v_lshl_add_u64 v[8:9], v[8:9], 0, s[6:7]
	s_lshl_b32 s9, s8, 13
	s_lshl_b32 s13, s12, 7
	s_waitcnt vmcnt(2)
	s_barrier
	global_load_lds_dwordx4 v[8:9], off
	v_lshl_add_u64 v[6:7], v[6:7], 0, s[6:7]
	s_add_i32 m0, s31, 0x1a000
	s_add_i32 s56, s31, 0x8000
	s_add_i32 s57, s31, 0xa000
	global_load_lds_dwordx4 v[6:7], off
	v_lshl_add_u64 v[2:3], v[2:3], 0, s[6:7]
	s_mov_b32 m0, s56
	s_add_u32 s10, s40, 0x40080
	global_load_lds_dwordx4 v[2:3], off
	v_lshl_add_u64 v[2:3], v[4:5], 0, s[6:7]
	s_mov_b32 m0, s57
	s_addc_u32 s11, s41, 0
	global_load_lds_dwordx4 v[2:3], off
	s_add_i32 m0, s31, 0x1c000
	v_lshl_add_u64 v[2:3], s[10:11], 0, v[146:147]
	global_load_lds_dwordx4 v[2:3], off
	v_lshl_add_u64 v[2:3], s[10:11], 0, v[150:151]
	s_add_i32 m0, s31, 0x1e000
	s_sext_i32_i8 s60, s0
	global_load_lds_dwordx4 v[2:3], off
	v_and_b32_e32 v2, 15, v0
	v_lshlrev_b32_e32 v3, 1, v12
	v_lshlrev_b32_e32 v4, 6, v0
	s_movk_i32 s0, 0x3c0
	v_lshlrev_b32_e32 v5, 2, v0
	v_lshlrev_b32_e32 v0, 8, v0
	v_and_or_b32 v4, v4, s0, v3
	v_lshl_or_b32 v166, s8, 6, v2
	v_lshl_or_b32 v2, v2, 6, v3
	v_and_b32_e32 v0, 0x18000, v0
	v_lshlrev_b32_e32 v3, 11, v11
	v_or3_b32 v0, v1, v0, v3
	v_add_u32_e32 v152, v0, v10
	v_lshlrev_b32_e32 v0, 4, v13
	v_and_b32_e32 v5, 32, v5
	s_waitcnt vmcnt(6)
	s_cmpk_lt_u32 s1, 0x100
	v_and_b32_e32 v0, 0x38000, v0
	v_bitop3_b32 v2, v2, s9, v5 bitop3:0xde
	v_bitop3_b32 v167, s13, v4, v5 bitop3:0xf6
	s_cselect_b64 s[8:9], -1, 0
	v_or3_b32 v0, v1, v0, v3
	s_add_i32 s58, 0, 0x10000
	s_add_i32 s59, 0, 0x14000
	v_or_b32_e32 v168, s12, v12
	v_mov_b32_e32 v153, v147
	v_add_u32_e32 v154, v0, v10
	v_mov_b32_e32 v155, v147
	v_mov_b64_e32 v[156:157], 0x500
	v_mov_b64_e32 v[158:159], 0x4ff
	v_add_u32_e32 v169, s58, v167
	v_add_u32_e32 v170, s59, v167
	v_add_u32_e32 v171, 0, v2
	s_mov_b64 s[10:11], 0x12000
	s_mov_b64 s[12:13], 0x80000
	s_mov_b64 s[14:15], 0x90000
	s_mov_b64 s[16:17], 0xa0000
	s_mov_b64 s[18:19], 0xb0000
	s_barrier
	s_cmp_ge_u32 s97, 4
	s_cbranch_scc0 .Lp4_prio
	s_setprio 1

; #define PG8_STAGE(bufoff, gbase, voff) do { _Pragma("unroll") for (int _i = 0; _i < 2; ++_i) \
;         __builtin_amdgcn_global_load_lds((const unsigned*)((const char*)(gbase) + (voff)[_i]), (PG8_LAS unsigned*)(lds + (bufoff) + ldsw + _i * 8192), 16, 0, 0); } while (0)
; #define PG8_LDA(dst, b, h) do { _Pragma("unroll") for (int m = 0; m < 4; ++m) _Pragma("unroll") for (int k = 0; k < 2; ++k) dst[m][k] = *(const PG8_LAS bf16x8*)(lds + PG8_SA(b, h) + aoff + m * 2048 + k * 1024); } while (0)
; #define PG8_LDB(dst, b, h) do { _Pragma("unroll") for (int n = 0; n < 2; ++n) _Pragma("unroll") for (int k = 0; k < 2; ++k) dst[n][k] = *(const PG8_LAS bf16x8*)(lds + PG8_SB(b, h) + boff + n * 2048 + k * 1024); } while (0)
; #define PG8_MMA(ai, bj, At, Bt) do { __builtin_amdgcn_s_setprio(1); _Pragma("unroll") for (int m = 0; m < 4; ++m) _Pragma("unroll") for (int n = 0; n < 2; ++n) _Pragma("unroll") for (int k = 0; k < 2; ++k) \
;         acc[ai][bj][m][n] = __builtin_amdgcn_mfma_f32_16x16x32_bf16(Bt[n][k], At[m][k], acc[ai][bj][m][n], 0, 0, 0); __builtin_amdgcn_s_setprio(0); } while (0)
; #define PG8_WAIT_V(n) asm volatile("s_waitcnt vmcnt(" #n ")" ::: "memory")
; #define PG8_WAIT_L(n) asm volatile("s_waitcnt lgkmcnt(" #n ")" ::: "memory")
; #define PG8_BAR __builtin_amdgcn_s_barrier()
; #define PG8_SCHED __builtin_amdgcn_sched_barrier(0)
; template <class Epi, class Sched, bool ALIGN_EPI = false, bool SP2 = false>
; __device__ __forceinline__ void gemm_phase(PG8_LAS unsigned char* lds, const Gemm g, const Sched& S, const Epi& E) {
;     ...
;             PG8_LDB(B0, 0, 0); PG8_LDB(B1, 0, 1); PG8_SCHED; PG8_LDA(At, 0, 0); PG8_STAGE(PG8_SA(1, 1), a1 + hstep, voffA);
;             PG8_WAIT_V(8); PG8_WAIT_L(0); PG8_BAR; PG8_MMA(0, 0, At, B0); PG8_MMA(0, 1, At, B1); PG8_BAR; PG8_SCHED;
;             PG8_LDA(At, 0, 1); PG8_STAGE(PG8_SB(0, 0), b2, voffB); PG8_STAGE(PG8_SB(0, 1), b2 + hstep, voffB); PG8_STAGE(PG8_SA(0, 0), a2, voffA);
;             PG8_WAIT_V(8); PG8_WAIT_L(0); PG8_BAR; PG8_MMA(1, 0, At, B0); PG8_MMA(1, 1, At, B1); PG8_BAR; PG8_SCHED;
.LBB0_457:
	ds_read_b128 v[128:131], v169
	ds_read_b128 v[132:135], v169 offset:1024
	ds_read_b128 v[136:139], v169 offset:2048
	ds_read_b128 v[140:143], v169 offset:3072
	ds_read_b128 v[160:163], v170
	ds_read_b128 v[172:175], v170 offset:1024
	ds_read_b128 v[176:179], v170 offset:2048
	ds_read_b128 v[180:183], v170 offset:3072
	s_add_u32 s38, s34, 0xfffc0080
	s_addc_u32 s39, s35, -1
	s_cmp_eq_u32 s65, 12
	s_cselect_b32 s41, s25, s39
	s_cselect_b32 s40, s61, s38
	s_cselect_b32 s39, s21, s64
	s_cselect_b32 s38, s62, s63
	v_lshl_add_u64 v[164:165], s[34:35], 0, v[152:153]
	s_add_i32 m0, s31, 0xc000
	ds_read_b128 v[184:187], v171
	ds_read_b128 v[188:191], v171 offset:1024
	ds_read_b128 v[192:195], v171 offset:2048
	ds_read_b128 v[196:199], v171 offset:3072
	ds_read_b128 v[200:203], v171 offset:4096
	ds_read_b128 v[204:207], v171 offset:5120
	ds_read_b128 v[208:211], v171 offset:6144
	ds_read_b128 v[212:215], v171 offset:7168
	global_load_lds_dwordx4 v[164:165], off
	v_lshl_add_u64 v[164:165], s[34:35], 0, v[154:155]
	s_add_i32 m0, s31, 0xe000
	s_nop 0
	global_load_lds_dwordx4 v[164:165], off
	s_waitcnt vmcnt(8)
	s_waitcnt lgkmcnt(0)
	s_barrier
	s_waitcnt lgkmcnt(0)
	v_mfma_f32_16x16x32_bf16 v[124:127], v[128:131], v[184:187], v[124:127]
	v_mfma_f32_16x16x32_bf16 v[120:123], v[136:139], v[184:187], v[120:123]
	v_mfma_f32_16x16x32_bf16 v[116:119], v[128:131], v[192:195], v[116:119]
	v_mfma_f32_16x16x32_bf16 v[112:115], v[136:139], v[192:195], v[112:115]
	v_mfma_f32_16x16x32_bf16 v[96:99], v[128:131], v[200:203], v[96:99]
	v_mfma_f32_16x16x32_bf16 v[88:91], v[136:139], v[200:203], v[88:91]
	v_mfma_f32_16x16x32_bf16 v[84:87], v[128:131], v[208:211], v[84:87]
	v_mfma_f32_16x16x32_bf16 v[76:79], v[136:139], v[208:211], v[76:79]
	v_mfma_f32_16x16x32_bf16 v[124:127], v[132:135], v[188:191], v[124:127]
	v_mfma_f32_16x16x32_bf16 v[120:123], v[140:143], v[188:191], v[120:123]
	v_mfma_f32_16x16x32_bf16 v[116:119], v[132:135], v[196:199], v[116:119]
	v_mfma_f32_16x16x32_bf16 v[112:115], v[140:143], v[196:199], v[112:115]
	v_mfma_f32_16x16x32_bf16 v[96:99], v[132:135], v[204:207], v[96:99]
	v_mfma_f32_16x16x32_bf16 v[88:91], v[140:143], v[204:207], v[88:91]
	v_mfma_f32_16x16x32_bf16 v[84:87], v[132:135], v[212:215], v[84:87]
	v_mfma_f32_16x16x32_bf16 v[76:79], v[140:143], v[212:215], v[76:79]
	v_mfma_f32_16x16x32_bf16 v[108:111], v[160:163], v[184:187], v[108:111]
	v_mfma_f32_16x16x32_bf16 v[104:107], v[176:179], v[184:187], v[104:107]
	v_mfma_f32_16x16x32_bf16 v[100:103], v[160:163], v[192:195], v[100:103]
	v_mfma_f32_16x16x32_bf16 v[92:95], v[176:179], v[192:195], v[92:95]
	v_mfma_f32_16x16x32_bf16 v[80:83], v[160:163], v[200:203], v[80:83]
	v_mfma_f32_16x16x32_bf16 v[72:75], v[176:179], v[200:203], v[72:75]
	v_mfma_f32_16x16x32_bf16 v[68:71], v[160:163], v[208:211], v[68:71]
	v_mfma_f32_16x16x32_bf16 v[64:67], v[176:179], v[208:211], v[64:67]
	v_mfma_f32_16x16x32_bf16 v[108:111], v[172:175], v[188:191], v[108:111]
	v_mfma_f32_16x16x32_bf16 v[104:107], v[180:183], v[188:191], v[104:107]
	v_mfma_f32_16x16x32_bf16 v[100:103], v[172:175], v[196:199], v[100:103]
	v_mfma_f32_16x16x32_bf16 v[92:95], v[180:183], v[196:199], v[92:95]
	v_mfma_f32_16x16x32_bf16 v[80:83], v[172:175], v[204:207], v[80:83]
	v_mfma_f32_16x16x32_bf16 v[72:75], v[180:183], v[204:207], v[72:75]
	v_mfma_f32_16x16x32_bf16 v[68:71], v[172:175], v[212:215], v[68:71]
	v_mfma_f32_16x16x32_bf16 v[64:67], v[180:183], v[212:215], v[64:67]
	s_barrier
	s_add_i32 s68, s58, s45
	v_lshl_add_u64 v[164:165], s[38:39], 0, v[146:147]
	s_mov_b32 m0, s68
	ds_read_b128 v[184:187], v171 offset:16384
	ds_read_b128 v[188:191], v171 offset:17408
	ds_read_b128 v[192:195], v171 offset:18432
	ds_read_b128 v[196:199], v171 offset:19456
	ds_read_b128 v[200:203], v171 offset:20480
	ds_read_b128 v[204:207], v171 offset:21504
	ds_read_b128 v[208:211], v171 offset:22528
	ds_read_b128 v[212:215], v171 offset:23552
	global_load_lds_dwordx4 v[164:165], off
	s_add_i32 m0, s68, 0x2000
	s_add_u32 s68, s38, 0x40000
	v_lshl_add_u64 v[216:217], s[38:39], 0, v[150:151]
	s_addc_u32 s69, s39, 0
	s_add_i32 s70, s59, s45
	global_load_lds_dwordx4 v[216:217], off
	v_lshl_add_u64 v[218:219], s[68:69], 0, v[146:147]
	s_mov_b32 m0, s70
	v_lshl_add_u64 v[220:221], s[40:41], 0, v[148:149]
	global_load_lds_dwordx4 v[218:219], off
	v_lshl_add_u64 v[218:219], s[68:69], 0, v[150:151]
	s_add_i32 m0, s70, 0x2000
	s_nop 0
	global_load_lds_dwordx4 v[218:219], off
	v_lshl_add_u64 v[218:219], s[40:41], 0, v[144:145]
	s_mov_b32 m0, s31
	s_nop 0
	global_load_lds_dwordx4 v[218:219], off
	s_mov_b32 m0, s48
	s_nop 0
	global_load_lds_dwordx4 v[220:221], off
	s_waitcnt vmcnt(8)
	s_waitcnt lgkmcnt(0)
	s_barrier
; #define PG8_STAGE(bufoff, gbase, voff) do { _Pragma("unroll") for (int _i = 0; _i < 2; ++_i) \
;         __builtin_amdgcn_global_load_lds((const unsigned*)((const char*)(gbase) + (voff)[_i]), (PG8_LAS unsigned*)(lds + (bufoff) + ldsw + _i * 8192), 16, 0, 0); } while (0)
; #define PG8_LDA(dst, b, h) do { _Pragma("unroll") for (int m = 0; m < 4; ++m) _Pragma("unroll") for (int k = 0; k < 2; ++k) dst[m][k] = *(const PG8_LAS bf16x8*)(lds + PG8_SA(b, h) + aoff + m * 2048 + k * 1024); } while (0)
; #define PG8_LDB(dst, b, h) do { _Pragma("unroll") for (int n = 0; n < 2; ++n) _Pragma("unroll") for (int k = 0; k < 2; ++k) dst[n][k] = *(const PG8_LAS bf16x8*)(lds + PG8_SB(b, h) + boff + n * 2048 + k * 1024); } while (0)
; #define PG8_MMA(ai, bj, At, Bt) do { __builtin_amdgcn_s_setprio(1); _Pragma("unroll") for (int m = 0; m < 4; ++m) _Pragma("unroll") for (int n = 0; n < 2; ++n) _Pragma("unroll") for (int k = 0; k < 2; ++k) \
;         acc[ai][bj][m][n] = __builtin_amdgcn_mfma_f32_16x16x32_bf16(Bt[n][k], At[m][k], acc[ai][bj][m][n], 0, 0, 0); __builtin_amdgcn_s_setprio(0); } while (0)
; #define PG8_WAIT_V(n) asm volatile("s_waitcnt vmcnt(" #n ")" ::: "memory")
; #define PG8_WAIT_L(n) asm volatile("s_waitcnt lgkmcnt(" #n ")" ::: "memory")
; #define PG8_BAR __builtin_amdgcn_s_barrier()
; #define PG8_SCHED __builtin_amdgcn_sched_barrier(0)
; template <class Epi, class Sched, bool ALIGN_EPI = false, bool SP2 = false>
; __device__ __forceinline__ void gemm_phase(PG8_LAS unsigned char* lds, const Gemm g, const Sched& S, const Epi& E) {
;     ...
;             PG8_WAIT_V(8); PG8_WAIT_L(0); PG8_BAR; PG8_MMA(1, 0, At, B0); PG8_MMA(1, 1, At, B1); PG8_BAR; PG8_SCHED;
;             PG8_LDB(B0, 1, 0); PG8_LDB(B1, 1, 1); PG8_SCHED; PG8_LDA(At, 1, 0); PG8_STAGE(PG8_SA(0, 1), a2 + hstep, voffA);
;             PG8_WAIT_V(8); PG8_WAIT_L(0); PG8_BAR; PG8_MMA(0, 0, At, B0); PG8_MMA(0, 1, At, B1); PG8_BAR; PG8_SCHED;
	s_waitcnt lgkmcnt(0)
	v_mfma_f32_16x16x32_bf16 v[60:63], v[128:131], v[184:187], v[60:63]
	v_mfma_f32_16x16x32_bf16 v[56:59], v[136:139], v[184:187], v[56:59]
	v_mfma_f32_16x16x32_bf16 v[52:55], v[128:131], v[192:195], v[52:55]
	v_mfma_f32_16x16x32_bf16 v[48:51], v[136:139], v[192:195], v[48:51]
	v_mfma_f32_16x16x32_bf16 v[36:39], v[128:131], v[200:203], v[36:39]
	v_mfma_f32_16x16x32_bf16 v[24:27], v[136:139], v[200:203], v[24:27]
	v_mfma_f32_16x16x32_bf16 v[20:23], v[128:131], v[208:211], v[20:23]
	v_mfma_f32_16x16x32_bf16 v[12:15], v[136:139], v[208:211], v[12:15]
	v_mfma_f32_16x16x32_bf16 v[60:63], v[132:135], v[188:191], v[60:63]
	v_mfma_f32_16x16x32_bf16 v[56:59], v[140:143], v[188:191], v[56:59]
	v_mfma_f32_16x16x32_bf16 v[52:55], v[132:135], v[196:199], v[52:55]
	v_mfma_f32_16x16x32_bf16 v[48:51], v[140:143], v[196:199], v[48:51]
	v_mfma_f32_16x16x32_bf16 v[36:39], v[132:135], v[204:207], v[36:39]
	v_mfma_f32_16x16x32_bf16 v[24:27], v[140:143], v[204:207], v[24:27]
	v_mfma_f32_16x16x32_bf16 v[20:23], v[132:135], v[212:215], v[20:23]
	v_mfma_f32_16x16x32_bf16 v[12:15], v[140:143], v[212:215], v[12:15]
	v_mfma_f32_16x16x32_bf16 v[44:47], v[160:163], v[184:187], v[44:47]
	v_mfma_f32_16x16x32_bf16 v[40:43], v[176:179], v[184:187], v[40:43]
	v_mfma_f32_16x16x32_bf16 v[32:35], v[160:163], v[192:195], v[32:35]
	v_mfma_f32_16x16x32_bf16 v[28:31], v[176:179], v[192:195], v[28:31]
	v_mfma_f32_16x16x32_bf16 v[16:19], v[160:163], v[200:203], v[16:19]
	v_mfma_f32_16x16x32_bf16 v[8:11], v[176:179], v[200:203], v[8:11]
	v_mfma_f32_16x16x32_bf16 v[4:7], v[160:163], v[208:211], v[4:7]
	v_mfma_f32_16x16x32_bf16 v[0:3], v[176:179], v[208:211], v[0:3]
	v_mfma_f32_16x16x32_bf16 v[44:47], v[172:175], v[188:191], v[44:47]
	v_mfma_f32_16x16x32_bf16 v[40:43], v[180:183], v[188:191], v[40:43]
	v_mfma_f32_16x16x32_bf16 v[32:35], v[172:175], v[196:199], v[32:35]
	v_mfma_f32_16x16x32_bf16 v[28:31], v[180:183], v[196:199], v[28:31]
	v_mfma_f32_16x16x32_bf16 v[16:19], v[172:175], v[204:207], v[16:19]
	v_mfma_f32_16x16x32_bf16 v[8:11], v[180:183], v[204:207], v[8:11]
	v_mfma_f32_16x16x32_bf16 v[4:7], v[172:175], v[212:215], v[4:7]
	v_mfma_f32_16x16x32_bf16 v[0:3], v[180:183], v[212:215], v[0:3]
	s_barrier
	s_add_i32 s68, 0, 0x18000
	s_add_i32 s69, 0, 0x1c000
	v_add_u32_e32 v140, s68, v167
	v_add_u32_e32 v180, s69, v167
	ds_read_b128 v[128:131], v140
	ds_read_b128 v[132:135], v140 offset:1024
	ds_read_b128 v[136:139], v140 offset:2048
	ds_read_b128 v[140:143], v140 offset:3072
	ds_read_b128 v[160:163], v180
	ds_read_b128 v[172:175], v180 offset:1024
	ds_read_b128 v[176:179], v180 offset:2048
	ds_read_b128 v[180:183], v180 offset:3072
	s_add_u32 s40, s40, 0x40000
	s_addc_u32 s41, s41, 0
	s_mov_b32 m0, s49
	v_lshl_add_u64 v[222:223], s[40:41], 0, v[144:145]
	ds_read_b128 v[184:187], v171 offset:32768
	ds_read_b128 v[188:191], v171 offset:33792
	ds_read_b128 v[192:195], v171 offset:34816
	ds_read_b128 v[196:199], v171 offset:35840
	ds_read_b128 v[200:203], v171 offset:36864
	ds_read_b128 v[204:207], v171 offset:37888
	ds_read_b128 v[208:211], v171 offset:38912
	ds_read_b128 v[212:215], v171 offset:39936
	global_load_lds_dwordx4 v[222:223], off
	v_lshl_add_u64 v[222:223], s[40:41], 0, v[148:149]
	s_mov_b32 m0, s50
	s_nop 0
	global_load_lds_dwordx4 v[222:223], off
	s_waitcnt vmcnt(8)
	s_waitcnt lgkmcnt(0)
	s_barrier
	s_waitcnt lgkmcnt(0)
	v_mfma_f32_16x16x32_bf16 v[124:127], v[128:131], v[184:187], v[124:127]
	v_mfma_f32_16x16x32_bf16 v[120:123], v[136:139], v[184:187], v[120:123]
	v_mfma_f32_16x16x32_bf16 v[116:119], v[128:131], v[192:195], v[116:119]
	v_mfma_f32_16x16x32_bf16 v[112:115], v[136:139], v[192:195], v[112:115]
	v_mfma_f32_16x16x32_bf16 v[96:99], v[128:131], v[200:203], v[96:99]
	v_mfma_f32_16x16x32_bf16 v[88:91], v[136:139], v[200:203], v[88:91]
	v_mfma_f32_16x16x32_bf16 v[84:87], v[128:131], v[208:211], v[84:87]
	v_mfma_f32_16x16x32_bf16 v[76:79], v[136:139], v[208:211], v[76:79]
	v_mfma_f32_16x16x32_bf16 v[124:127], v[132:135], v[188:191], v[124:127]
	v_mfma_f32_16x16x32_bf16 v[120:123], v[140:143], v[188:191], v[120:123]
	v_mfma_f32_16x16x32_bf16 v[116:119], v[132:135], v[196:199], v[116:119]
	v_mfma_f32_16x16x32_bf16 v[112:115], v[140:143], v[196:199], v[112:115]
	v_mfma_f32_16x16x32_bf16 v[96:99], v[132:135], v[204:207], v[96:99]
	v_mfma_f32_16x16x32_bf16 v[88:91], v[140:143], v[204:207], v[88:91]
	v_mfma_f32_16x16x32_bf16 v[84:87], v[132:135], v[212:215], v[84:87]
	v_mfma_f32_16x16x32_bf16 v[76:79], v[140:143], v[212:215], v[76:79]
	v_mfma_f32_16x16x32_bf16 v[108:111], v[160:163], v[184:187], v[108:111]
	v_mfma_f32_16x16x32_bf16 v[104:107], v[176:179], v[184:187], v[104:107]
	v_mfma_f32_16x16x32_bf16 v[100:103], v[160:163], v[192:195], v[100:103]
	v_mfma_f32_16x16x32_bf16 v[92:95], v[176:179], v[192:195], v[92:95]
	v_mfma_f32_16x16x32_bf16 v[80:83], v[160:163], v[200:203], v[80:83]
	v_mfma_f32_16x16x32_bf16 v[72:75], v[176:179], v[200:203], v[72:75]
	v_mfma_f32_16x16x32_bf16 v[68:71], v[160:163], v[208:211], v[68:71]
	v_mfma_f32_16x16x32_bf16 v[64:67], v[176:179], v[208:211], v[64:67]
	v_mfma_f32_16x16x32_bf16 v[108:111], v[172:175], v[188:191], v[108:111]
	v_mfma_f32_16x16x32_bf16 v[104:107], v[180:183], v[188:191], v[104:107]
	v_mfma_f32_16x16x32_bf16 v[100:103], v[172:175], v[196:199], v[100:103]
	v_mfma_f32_16x16x32_bf16 v[92:95], v[180:183], v[196:199], v[92:95]
	v_mfma_f32_16x16x32_bf16 v[80:83], v[172:175], v[204:207], v[80:83]
	v_mfma_f32_16x16x32_bf16 v[72:75], v[180:183], v[204:207], v[72:75]
	v_mfma_f32_16x16x32_bf16 v[68:71], v[172:175], v[212:215], v[68:71]
	v_mfma_f32_16x16x32_bf16 v[64:67], v[180:183], v[212:215], v[64:67]
	s_barrier
; #define PG8_STAGE(bufoff, gbase, voff) do { _Pragma("unroll") for (int _i = 0; _i < 2; ++_i) \
;         __builtin_amdgcn_global_load_lds((const unsigned*)((const char*)(gbase) + (voff)[_i]), (PG8_LAS unsigned*)(lds + (bufoff) + ldsw + _i * 8192), 16, 0, 0); } while (0)
; #define PG8_LDA(dst, b, h) do { _Pragma("unroll") for (int m = 0; m < 4; ++m) _Pragma("unroll") for (int k = 0; k < 2; ++k) dst[m][k] = *(const PG8_LAS bf16x8*)(lds + PG8_SA(b, h) + aoff + m * 2048 + k * 1024); } while (0)
; #define PG8_LDB(dst, b, h) do { _Pragma("unroll") for (int n = 0; n < 2; ++n) _Pragma("unroll") for (int k = 0; k < 2; ++k) dst[n][k] = *(const PG8_LAS bf16x8*)(lds + PG8_SB(b, h) + boff + n * 2048 + k * 1024); } while (0)
; template <class Epi, class Sched, bool ALIGN_EPI = false, bool SP2 = false>
; __device__ __forceinline__ void gemm_phase(PG8_LAS unsigned char* lds, const Gemm g, const Sched& S, const Epi& E) {
;     ...
;         for (int t = 0; t < nt; t += 2) {
;             const bool last = (t == nt - 2);
;             const char* a1 = cA + (size_t)(t + 1) * kstep;
;             const char* a2 = last ? nA : cA + (size_t)(t + 2) * kstep; const char* b2 = last ? nB : cB + (size_t)(t + 2) * kstep;
;             const char* a3 = a2 + kstep; const char* b3 = b2 + kstep;
;             if (last && has_next) S.a_ready(nxt);
;             if constexpr (SP2) {
;             PG8_LDB(B0, 0, 0); PG8_LDB(B1, 0, 1); PG8_SCHED; PG8_LDA(At, 0, 0); PG8_STAGE(PG8_SA(1, 1), a1 + hstep, voffA);
;             PG8_WAIT_V(8); PG8_WAIT_L(0); PG8_BAR; PG8_MMA(0, 0, At, B0); PG8_MMA(0, 1, At, B1); PG8_BAR; PG8_SCHED;
;             PG8_LDA(At, 0, 1); PG8_STAGE(PG8_SB(0, 0), b2, voffB); PG8_STAGE(PG8_SB(0, 1), b2 + hstep, voffB); PG8_STAGE(PG8_SA(0, 0), a2, voffA);
;             PG8_WAIT_V(8); PG8_WAIT_L(0); PG8_BAR; PG8_MMA(1, 0, At, B0); PG8_MMA(1, 1, At, B1); PG8_BAR; PG8_SCHED;
;             PG8_LDB(B0, 1, 0); PG8_LDB(B1, 1, 1); PG8_SCHED; PG8_LDA(At, 1, 0); PG8_STAGE(PG8_SA(0, 1), a2 + hstep, voffA);
;             PG8_WAIT_V(8); PG8_WAIT_L(0); PG8_BAR; PG8_MMA(0, 0, At, B0); PG8_MMA(0, 1, At, B1); PG8_BAR; PG8_SCHED;
;             PG8_LDA(At, 1, 1); PG8_STAGE(PG8_SB(1, 0), b3, voffB); PG8_STAGE(PG8_SB(1, 1), b3 + hstep, voffB); PG8_STAGE(PG8_SA(1, 0), a3, voffA);
;             PG8_WAIT_V(8); PG8_WAIT_L(0); PG8_BAR; PG8_MMA(1, 0, At, B0); PG8_MMA(1, 1, At, B1); PG8_BAR; PG8_SCHED;
	s_add_i32 s40, s68, s45
	v_lshl_add_u64 v[164:165], v[164:165], 0, s[6:7]
	s_mov_b32 m0, s40
	ds_read_b128 v[184:187], v171 offset:49152
	ds_read_b128 v[188:191], v171 offset:50176
	ds_read_b128 v[192:195], v171 offset:51200
	ds_read_b128 v[196:199], v171 offset:52224
	ds_read_b128 v[200:203], v171 offset:53248
	ds_read_b128 v[204:207], v171 offset:54272
	ds_read_b128 v[208:211], v171 offset:55296
	ds_read_b128 v[212:215], v171 offset:56320
	global_load_lds_dwordx4 v[164:165], off
	s_add_i32 m0, s40, 0x2000
	s_add_u32 s38, s38, 0x40080
	v_lshl_add_u64 v[164:165], v[216:217], 0, s[6:7]
	s_addc_u32 s39, s39, 0
	s_add_i32 s40, s69, s45
	global_load_lds_dwordx4 v[164:165], off
	v_lshl_add_u64 v[164:165], s[38:39], 0, v[146:147]
	s_mov_b32 m0, s40
	s_nop 0
	global_load_lds_dwordx4 v[164:165], off
	v_lshl_add_u64 v[164:165], s[38:39], 0, v[150:151]
	s_add_i32 m0, s40, 0x2000
	s_nop 0
	global_load_lds_dwordx4 v[164:165], off
	v_lshl_add_u64 v[164:165], v[218:219], 0, s[6:7]
	s_mov_b32 m0, s56
	s_nop 0
	global_load_lds_dwordx4 v[164:165], off
	v_lshl_add_u64 v[164:165], v[220:221], 0, s[6:7]
	s_mov_b32 m0, s57
	s_nop 0
	global_load_lds_dwordx4 v[164:165], off
	s_waitcnt vmcnt(8)
	s_waitcnt lgkmcnt(0)
	s_barrier
	s_waitcnt lgkmcnt(0)
	v_mfma_f32_16x16x32_bf16 v[60:63], v[128:131], v[184:187], v[60:63]
	v_mfma_f32_16x16x32_bf16 v[56:59], v[136:139], v[184:187], v[56:59]
	v_mfma_f32_16x16x32_bf16 v[52:55], v[128:131], v[192:195], v[52:55]
	v_mfma_f32_16x16x32_bf16 v[48:51], v[136:139], v[192:195], v[48:51]
	v_mfma_f32_16x16x32_bf16 v[36:39], v[128:131], v[200:203], v[36:39]
	v_mfma_f32_16x16x32_bf16 v[24:27], v[136:139], v[200:203], v[24:27]
	v_mfma_f32_16x16x32_bf16 v[20:23], v[128:131], v[208:211], v[20:23]
	v_mfma_f32_16x16x32_bf16 v[12:15], v[136:139], v[208:211], v[12:15]
	v_mfma_f32_16x16x32_bf16 v[60:63], v[132:135], v[188:191], v[60:63]
	v_mfma_f32_16x16x32_bf16 v[56:59], v[140:143], v[188:191], v[56:59]
	v_mfma_f32_16x16x32_bf16 v[52:55], v[132:135], v[196:199], v[52:55]
	v_mfma_f32_16x16x32_bf16 v[48:51], v[140:143], v[196:199], v[48:51]
	v_mfma_f32_16x16x32_bf16 v[36:39], v[132:135], v[204:207], v[36:39]
	v_mfma_f32_16x16x32_bf16 v[24:27], v[140:143], v[204:207], v[24:27]
	v_mfma_f32_16x16x32_bf16 v[20:23], v[132:135], v[212:215], v[20:23]
	v_mfma_f32_16x16x32_bf16 v[12:15], v[140:143], v[212:215], v[12:15]
	v_mfma_f32_16x16x32_bf16 v[44:47], v[160:163], v[184:187], v[44:47]
	v_mfma_f32_16x16x32_bf16 v[40:43], v[176:179], v[184:187], v[40:43]
	v_mfma_f32_16x16x32_bf16 v[32:35], v[160:163], v[192:195], v[32:35]
	v_mfma_f32_16x16x32_bf16 v[28:31], v[176:179], v[192:195], v[28:31]
	v_mfma_f32_16x16x32_bf16 v[16:19], v[160:163], v[200:203], v[16:19]
	v_mfma_f32_16x16x32_bf16 v[8:11], v[176:179], v[200:203], v[8:11]
	v_mfma_f32_16x16x32_bf16 v[4:7], v[160:163], v[208:211], v[4:7]
	v_mfma_f32_16x16x32_bf16 v[0:3], v[176:179], v[208:211], v[0:3]
	v_mfma_f32_16x16x32_bf16 v[44:47], v[172:175], v[188:191], v[44:47]
	v_mfma_f32_16x16x32_bf16 v[40:43], v[180:183], v[188:191], v[40:43]
	v_mfma_f32_16x16x32_bf16 v[32:35], v[172:175], v[196:199], v[32:35]
	v_mfma_f32_16x16x32_bf16 v[28:31], v[180:183], v[196:199], v[28:31]
	v_mfma_f32_16x16x32_bf16 v[16:19], v[172:175], v[204:207], v[16:19]
	v_mfma_f32_16x16x32_bf16 v[8:11], v[180:183], v[204:207], v[8:11]
	v_mfma_f32_16x16x32_bf16 v[4:7], v[172:175], v[212:215], v[4:7]
	v_mfma_f32_16x16x32_bf16 v[0:3], v[180:183], v[212:215], v[0:3]
	s_add_i32 s65, s65, 2
	s_add_u32 s34, s34, 0x100
	s_addc_u32 s35, s35, 0
	s_add_u32 s63, s63, 0x100
	s_addc_u32 s64, s64, 0
	s_cmp_gt_u32 s65, 13
	s_cbranch_scc1 .Lp4_kexit
	s_barrier
	s_branch .LBB0_457

; #define PG8_STAGE(bufoff, gbase, voff) do { _Pragma("unroll") for (int _i = 0; _i < 2; ++_i) \
;         __builtin_amdgcn_global_load_lds((const unsigned*)((const char*)(gbase) + (voff)[_i]), (PG8_LAS unsigned*)(lds + (bufoff) + ldsw + _i * 8192), 16, 0, 0); } while (0)
; #define PG8_LDA(dst, b, h) do { _Pragma("unroll") for (int m = 0; m < 4; ++m) _Pragma("unroll") for (int k = 0; k < 2; ++k) dst[m][k] = *(const PG8_LAS bf16x8*)(lds + PG8_SA(b, h) + aoff + m * 2048 + k * 1024); } while (0)
; #define PG8_LDB(dst, b, h) do { _Pragma("unroll") for (int n = 0; n < 2; ++n) _Pragma("unroll") for (int k = 0; k < 2; ++k) dst[n][k] = *(const PG8_LAS bf16x8*)(lds + PG8_SB(b, h) + boff + n * 2048 + k * 1024); } while (0)
; #define PG8_MMA(ai, bj, At, Bt) do { __builtin_amdgcn_s_setprio(1); _Pragma("unroll") for (int m = 0; m < 4; ++m) _Pragma("unroll") for (int n = 0; n < 2; ++n) _Pragma("unroll") for (int k = 0; k < 2; ++k) \
;         acc[ai][bj][m][n] = __builtin_amdgcn_mfma_f32_16x16x32_bf16(Bt[n][k], At[m][k], acc[ai][bj][m][n], 0, 0, 0); __builtin_amdgcn_s_setprio(0); } while (0)
; #define PG8_WAIT_V(n) asm volatile("s_waitcnt vmcnt(" #n ")" ::: "memory")
; #define PG8_WAIT_L(n) asm volatile("s_waitcnt lgkmcnt(" #n ")" ::: "memory")
; #define PG8_BAR __builtin_amdgcn_s_barrier()
; #define PG8_SCHED __builtin_amdgcn_sched_barrier(0)
; template <class Epi, class Sched, bool ALIGN_EPI = false, bool SP2 = false>
; __device__ __forceinline__ void gemm_phase(PG8_LAS unsigned char* lds, const Gemm g, const Sched& S, const Epi& E) {
;     ...
;             PG8_LDB(B0, 0, 0); PG8_LDB(B1, 0, 1); PG8_SCHED; PG8_LDA(At, 0, 0); PG8_STAGE(PG8_SA(1, 1), a1 + hstep, voffA);
;             PG8_WAIT_V(8); PG8_WAIT_L(0); PG8_BAR; PG8_MMA(0, 0, At, B0); PG8_MMA(0, 1, At, B1); PG8_BAR; PG8_SCHED;
;             PG8_LDA(At, 0, 1); PG8_STAGE(PG8_SB(0, 0), b2, voffB); PG8_STAGE(PG8_SB(0, 1), b2 + hstep, voffB); PG8_STAGE(PG8_SA(0, 0), a2, voffA);
;             PG8_WAIT_V(8); PG8_WAIT_L(0); PG8_BAR; PG8_MMA(1, 0, At, B0); PG8_MMA(1, 1, At, B1); PG8_BAR; PG8_SCHED;
.Lp4_peel:
	ds_read_b128 v[128:131], v169
	ds_read_b128 v[132:135], v169 offset:1024
	ds_read_b128 v[136:139], v169 offset:2048
	ds_read_b128 v[140:143], v169 offset:3072
	ds_read_b128 v[160:163], v170
	ds_read_b128 v[172:175], v170 offset:1024
	ds_read_b128 v[176:179], v170 offset:2048
	ds_read_b128 v[180:183], v170 offset:3072
	s_add_u32 s38, s34, 0xfffc0080
	s_addc_u32 s39, s35, -1
	s_cmp_eq_u32 s65, 12
	s_cselect_b32 s41, s25, s39
	s_cselect_b32 s40, s61, s38
	s_cselect_b32 s39, s21, s64
	s_cselect_b32 s38, s62, s63
	ds_read_b128 v[184:187], v171
	ds_read_b128 v[188:191], v171 offset:1024
	ds_read_b128 v[192:195], v171 offset:2048
	ds_read_b128 v[196:199], v171 offset:3072
	ds_read_b128 v[200:203], v171 offset:4096
	ds_read_b128 v[204:207], v171 offset:5120
	ds_read_b128 v[208:211], v171 offset:6144
	ds_read_b128 v[212:215], v171 offset:7168
	s_waitcnt vmcnt(24)
	s_waitcnt lgkmcnt(0)
	s_barrier
	s_waitcnt lgkmcnt(0)
	v_mfma_f32_16x16x32_bf16 v[124:127], v[128:131], v[184:187], 0
	v_mfma_f32_16x16x32_bf16 v[120:123], v[136:139], v[184:187], 0
	v_mfma_f32_16x16x32_bf16 v[116:119], v[128:131], v[192:195], 0
	v_mfma_f32_16x16x32_bf16 v[112:115], v[136:139], v[192:195], 0
	v_mfma_f32_16x16x32_bf16 v[96:99], v[128:131], v[200:203], 0
	v_mfma_f32_16x16x32_bf16 v[88:91], v[136:139], v[200:203], 0
	v_mfma_f32_16x16x32_bf16 v[84:87], v[128:131], v[208:211], 0
	v_mfma_f32_16x16x32_bf16 v[76:79], v[136:139], v[208:211], 0
	v_mfma_f32_16x16x32_bf16 v[124:127], v[132:135], v[188:191], v[124:127]
	v_mfma_f32_16x16x32_bf16 v[120:123], v[140:143], v[188:191], v[120:123]
	v_mfma_f32_16x16x32_bf16 v[116:119], v[132:135], v[196:199], v[116:119]
	v_mfma_f32_16x16x32_bf16 v[112:115], v[140:143], v[196:199], v[112:115]
	v_mfma_f32_16x16x32_bf16 v[96:99], v[132:135], v[204:207], v[96:99]
	v_mfma_f32_16x16x32_bf16 v[88:91], v[140:143], v[204:207], v[88:91]
	v_mfma_f32_16x16x32_bf16 v[84:87], v[132:135], v[212:215], v[84:87]
	v_mfma_f32_16x16x32_bf16 v[76:79], v[140:143], v[212:215], v[76:79]
	v_mfma_f32_16x16x32_bf16 v[108:111], v[160:163], v[184:187], 0
	v_mfma_f32_16x16x32_bf16 v[104:107], v[176:179], v[184:187], 0
	v_mfma_f32_16x16x32_bf16 v[100:103], v[160:163], v[192:195], 0
	v_mfma_f32_16x16x32_bf16 v[92:95], v[176:179], v[192:195], 0
	v_mfma_f32_16x16x32_bf16 v[80:83], v[160:163], v[200:203], 0
	v_mfma_f32_16x16x32_bf16 v[72:75], v[176:179], v[200:203], 0
	v_mfma_f32_16x16x32_bf16 v[68:71], v[160:163], v[208:211], 0
	v_mfma_f32_16x16x32_bf16 v[64:67], v[176:179], v[208:211], 0
	v_mfma_f32_16x16x32_bf16 v[108:111], v[172:175], v[188:191], v[108:111]
	v_mfma_f32_16x16x32_bf16 v[104:107], v[180:183], v[188:191], v[104:107]
	v_mfma_f32_16x16x32_bf16 v[100:103], v[172:175], v[196:199], v[100:103]
	v_mfma_f32_16x16x32_bf16 v[92:95], v[180:183], v[196:199], v[92:95]
	v_mfma_f32_16x16x32_bf16 v[80:83], v[172:175], v[204:207], v[80:83]
	v_mfma_f32_16x16x32_bf16 v[72:75], v[180:183], v[204:207], v[72:75]
	v_mfma_f32_16x16x32_bf16 v[68:71], v[172:175], v[212:215], v[68:71]
	v_mfma_f32_16x16x32_bf16 v[64:67], v[180:183], v[212:215], v[64:67]
	s_barrier
	s_add_i32 s68, s58, s45
	v_lshl_add_u64 v[164:165], s[38:39], 0, v[146:147]
	s_mov_b32 m0, s68
	ds_read_b128 v[184:187], v171 offset:16384
	ds_read_b128 v[188:191], v171 offset:17408
	ds_read_b128 v[192:195], v171 offset:18432
	ds_read_b128 v[196:199], v171 offset:19456
	ds_read_b128 v[200:203], v171 offset:20480
	ds_read_b128 v[204:207], v171 offset:21504
	ds_read_b128 v[208:211], v171 offset:22528
	ds_read_b128 v[212:215], v171 offset:23552
	global_load_lds_dwordx4 v[164:165], off
	s_add_i32 m0, s68, 0x2000
	s_add_u32 s68, s38, 0x40000
	v_lshl_add_u64 v[216:217], s[38:39], 0, v[150:151]
	s_addc_u32 s69, s39, 0
	s_add_i32 s70, s59, s45
	global_load_lds_dwordx4 v[216:217], off
	v_lshl_add_u64 v[218:219], s[68:69], 0, v[146:147]
	s_mov_b32 m0, s70
	v_lshl_add_u64 v[220:221], s[40:41], 0, v[148:149]
	global_load_lds_dwordx4 v[218:219], off
	v_lshl_add_u64 v[218:219], s[68:69], 0, v[150:151]
	s_add_i32 m0, s70, 0x2000
	s_nop 0
	global_load_lds_dwordx4 v[218:219], off
	v_lshl_add_u64 v[218:219], s[40:41], 0, v[144:145]
	s_mov_b32 m0, s31
	s_nop 0
	global_load_lds_dwordx4 v[218:219], off
	s_mov_b32 m0, s48
	s_nop 0
	global_load_lds_dwordx4 v[220:221], off
	s_waitcnt vmcnt(24)
	s_waitcnt lgkmcnt(0)
	s_barrier
	s_waitcnt lgkmcnt(0)
	v_mfma_f32_16x16x32_bf16 v[60:63], v[128:131], v[184:187], 0
	v_mfma_f32_16x16x32_bf16 v[56:59], v[136:139], v[184:187], 0
	v_mfma_f32_16x16x32_bf16 v[52:55], v[128:131], v[192:195], 0
	v_mfma_f32_16x16x32_bf16 v[48:51], v[136:139], v[192:195], 0
	v_mfma_f32_16x16x32_bf16 v[36:39], v[128:131], v[200:203], 0
	v_mfma_f32_16x16x32_bf16 v[24:27], v[136:139], v[200:203], 0
	v_mfma_f32_16x16x32_bf16 v[20:23], v[128:131], v[208:211], 0
	v_mfma_f32_16x16x32_bf16 v[12:15], v[136:139], v[208:211], 0
	v_mfma_f32_16x16x32_bf16 v[60:63], v[132:135], v[188:191], v[60:63]
	v_mfma_f32_16x16x32_bf16 v[56:59], v[140:143], v[188:191], v[56:59]
	v_mfma_f32_16x16x32_bf16 v[52:55], v[132:135], v[196:199], v[52:55]
	v_mfma_f32_16x16x32_bf16 v[48:51], v[140:143], v[196:199], v[48:51]
	v_mfma_f32_16x16x32_bf16 v[36:39], v[132:135], v[204:207], v[36:39]
	v_mfma_f32_16x16x32_bf16 v[24:27], v[140:143], v[204:207], v[24:27]
	v_mfma_f32_16x16x32_bf16 v[20:23], v[132:135], v[212:215], v[20:23]
	v_mfma_f32_16x16x32_bf16 v[12:15], v[140:143], v[212:215], v[12:15]
	v_mfma_f32_16x16x32_bf16 v[44:47], v[160:163], v[184:187], 0
	v_mfma_f32_16x16x32_bf16 v[40:43], v[176:179], v[184:187], 0
	v_mfma_f32_16x16x32_bf16 v[32:35], v[160:163], v[192:195], 0
	v_mfma_f32_16x16x32_bf16 v[28:31], v[176:179], v[192:195], 0
	v_mfma_f32_16x16x32_bf16 v[16:19], v[160:163], v[200:203], 0
	v_mfma_f32_16x16x32_bf16 v[8:11], v[176:179], v[200:203], 0
	v_mfma_f32_16x16x32_bf16 v[4:7], v[160:163], v[208:211], 0
	v_mfma_f32_16x16x32_bf16 v[0:3], v[176:179], v[208:211], 0
	v_mfma_f32_16x16x32_bf16 v[44:47], v[172:175], v[188:191], v[44:47]
	v_mfma_f32_16x16x32_bf16 v[40:43], v[180:183], v[188:191], v[40:43]
	v_mfma_f32_16x16x32_bf16 v[32:35], v[172:175], v[196:199], v[32:35]
	v_mfma_f32_16x16x32_bf16 v[28:31], v[180:183], v[196:199], v[28:31]
	v_mfma_f32_16x16x32_bf16 v[16:19], v[172:175], v[204:207], v[16:19]
	v_mfma_f32_16x16x32_bf16 v[8:11], v[180:183], v[204:207], v[8:11]
	v_mfma_f32_16x16x32_bf16 v[4:7], v[172:175], v[212:215], v[4:7]
	v_mfma_f32_16x16x32_bf16 v[0:3], v[180:183], v[212:215], v[0:3]
	s_barrier
; #define PG8_STAGE(bufoff, gbase, voff) do { _Pragma("unroll") for (int _i = 0; _i < 2; ++_i) \
;         __builtin_amdgcn_global_load_lds((const unsigned*)((const char*)(gbase) + (voff)[_i]), (PG8_LAS unsigned*)(lds + (bufoff) + ldsw + _i * 8192), 16, 0, 0); } while (0)
; #define PG8_LDA(dst, b, h) do { _Pragma("unroll") for (int m = 0; m < 4; ++m) _Pragma("unroll") for (int k = 0; k < 2; ++k) dst[m][k] = *(const PG8_LAS bf16x8*)(lds + PG8_SA(b, h) + aoff + m * 2048 + k * 1024); } while (0)
; #define PG8_LDB(dst, b, h) do { _Pragma("unroll") for (int n = 0; n < 2; ++n) _Pragma("unroll") for (int k = 0; k < 2; ++k) dst[n][k] = *(const PG8_LAS bf16x8*)(lds + PG8_SB(b, h) + boff + n * 2048 + k * 1024); } while (0)
; #define PG8_MMA(ai, bj, At, Bt) do { __builtin_amdgcn_s_setprio(1); _Pragma("unroll") for (int m = 0; m < 4; ++m) _Pragma("unroll") for (int n = 0; n < 2; ++n) _Pragma("unroll") for (int k = 0; k < 2; ++k) \
;         acc[ai][bj][m][n] = __builtin_amdgcn_mfma_f32_16x16x32_bf16(Bt[n][k], At[m][k], acc[ai][bj][m][n], 0, 0, 0); __builtin_amdgcn_s_setprio(0); } while (0)
; #define PG8_WAIT_V(n) asm volatile("s_waitcnt vmcnt(" #n ")" ::: "memory")
; #define PG8_WAIT_L(n) asm volatile("s_waitcnt lgkmcnt(" #n ")" ::: "memory")
; #define PG8_BAR __builtin_amdgcn_s_barrier()
; #define PG8_SCHED __builtin_amdgcn_sched_barrier(0)
; template <class Epi, class Sched, bool ALIGN_EPI = false, bool SP2 = false>
; __device__ __forceinline__ void gemm_phase(PG8_LAS unsigned char* lds, const Gemm g, const Sched& S, const Epi& E) {
;     ...
;             PG8_LDB(B0, 1, 0); PG8_LDB(B1, 1, 1); PG8_SCHED; PG8_LDA(At, 1, 0); PG8_STAGE(PG8_SA(0, 1), a2 + hstep, voffA);
;             PG8_WAIT_V(8); PG8_WAIT_L(0); PG8_BAR; PG8_MMA(0, 0, At, B0); PG8_MMA(0, 1, At, B1); PG8_BAR; PG8_SCHED;
;             PG8_LDA(At, 1, 1); PG8_STAGE(PG8_SB(1, 0), b3, voffB); PG8_STAGE(PG8_SB(1, 1), b3 + hstep, voffB); PG8_STAGE(PG8_SA(1, 0), a3, voffA);
;             PG8_WAIT_V(8); PG8_WAIT_L(0); PG8_BAR; PG8_MMA(1, 0, At, B0); PG8_MMA(1, 1, At, B1); PG8_BAR; PG8_SCHED;
	s_add_i32 s68, 0, 0x18000
	s_add_i32 s69, 0, 0x1c000
	v_add_u32_e32 v140, s68, v167
	v_add_u32_e32 v180, s69, v167
	ds_read_b128 v[128:131], v140
	ds_read_b128 v[132:135], v140 offset:1024
	ds_read_b128 v[136:139], v140 offset:2048
	ds_read_b128 v[140:143], v140 offset:3072
	ds_read_b128 v[160:163], v180
	ds_read_b128 v[172:175], v180 offset:1024
	ds_read_b128 v[176:179], v180 offset:2048
	ds_read_b128 v[180:183], v180 offset:3072
	s_add_u32 s40, s40, 0x40000
	s_addc_u32 s41, s41, 0
	s_mov_b32 m0, s49
	v_lshl_add_u64 v[222:223], s[40:41], 0, v[144:145]
	ds_read_b128 v[184:187], v171 offset:32768
	ds_read_b128 v[188:191], v171 offset:33792
	ds_read_b128 v[192:195], v171 offset:34816
	ds_read_b128 v[196:199], v171 offset:35840
	ds_read_b128 v[200:203], v171 offset:36864
	ds_read_b128 v[204:207], v171 offset:37888
	ds_read_b128 v[208:211], v171 offset:38912
	ds_read_b128 v[212:215], v171 offset:39936
	global_load_lds_dwordx4 v[222:223], off
	v_lshl_add_u64 v[222:223], s[40:41], 0, v[148:149]
	s_mov_b32 m0, s50
	s_nop 0
	global_load_lds_dwordx4 v[222:223], off
	s_waitcnt vmcnt(24)
	s_waitcnt lgkmcnt(0)
	s_barrier
	s_waitcnt lgkmcnt(0)
	v_mfma_f32_16x16x32_bf16 v[124:127], v[128:131], v[184:187], v[124:127]
	v_mfma_f32_16x16x32_bf16 v[120:123], v[136:139], v[184:187], v[120:123]
	v_mfma_f32_16x16x32_bf16 v[116:119], v[128:131], v[192:195], v[116:119]
	v_mfma_f32_16x16x32_bf16 v[112:115], v[136:139], v[192:195], v[112:115]
	v_mfma_f32_16x16x32_bf16 v[96:99], v[128:131], v[200:203], v[96:99]
	v_mfma_f32_16x16x32_bf16 v[88:91], v[136:139], v[200:203], v[88:91]
	v_mfma_f32_16x16x32_bf16 v[84:87], v[128:131], v[208:211], v[84:87]
	v_mfma_f32_16x16x32_bf16 v[76:79], v[136:139], v[208:211], v[76:79]
	v_mfma_f32_16x16x32_bf16 v[124:127], v[132:135], v[188:191], v[124:127]
	v_mfma_f32_16x16x32_bf16 v[120:123], v[140:143], v[188:191], v[120:123]
	v_mfma_f32_16x16x32_bf16 v[116:119], v[132:135], v[196:199], v[116:119]
	v_mfma_f32_16x16x32_bf16 v[112:115], v[140:143], v[196:199], v[112:115]
	v_mfma_f32_16x16x32_bf16 v[96:99], v[132:135], v[204:207], v[96:99]
	v_mfma_f32_16x16x32_bf16 v[88:91], v[140:143], v[204:207], v[88:91]
	v_mfma_f32_16x16x32_bf16 v[84:87], v[132:135], v[212:215], v[84:87]
	v_mfma_f32_16x16x32_bf16 v[76:79], v[140:143], v[212:215], v[76:79]
	v_mfma_f32_16x16x32_bf16 v[108:111], v[160:163], v[184:187], v[108:111]
	v_mfma_f32_16x16x32_bf16 v[104:107], v[176:179], v[184:187], v[104:107]
	v_mfma_f32_16x16x32_bf16 v[100:103], v[160:163], v[192:195], v[100:103]
	v_mfma_f32_16x16x32_bf16 v[92:95], v[176:179], v[192:195], v[92:95]
	v_mfma_f32_16x16x32_bf16 v[80:83], v[160:163], v[200:203], v[80:83]
	v_mfma_f32_16x16x32_bf16 v[72:75], v[176:179], v[200:203], v[72:75]
	v_mfma_f32_16x16x32_bf16 v[68:71], v[160:163], v[208:211], v[68:71]
	v_mfma_f32_16x16x32_bf16 v[64:67], v[176:179], v[208:211], v[64:67]
	v_mfma_f32_16x16x32_bf16 v[108:111], v[172:175], v[188:191], v[108:111]
	v_mfma_f32_16x16x32_bf16 v[104:107], v[180:183], v[188:191], v[104:107]
	v_mfma_f32_16x16x32_bf16 v[100:103], v[172:175], v[196:199], v[100:103]
	v_mfma_f32_16x16x32_bf16 v[92:95], v[180:183], v[196:199], v[92:95]
	v_mfma_f32_16x16x32_bf16 v[80:83], v[172:175], v[204:207], v[80:83]
	v_mfma_f32_16x16x32_bf16 v[72:75], v[180:183], v[204:207], v[72:75]
	v_mfma_f32_16x16x32_bf16 v[68:71], v[172:175], v[212:215], v[68:71]
	v_mfma_f32_16x16x32_bf16 v[64:67], v[180:183], v[212:215], v[64:67]
	s_barrier
	s_add_i32 s40, s68, s45
	v_lshl_add_u64 v[164:165], v[164:165], 0, s[6:7]
	s_mov_b32 m0, s40
	ds_read_b128 v[184:187], v171 offset:49152
	ds_read_b128 v[188:191], v171 offset:50176
	ds_read_b128 v[192:195], v171 offset:51200
	ds_read_b128 v[196:199], v171 offset:52224
	ds_read_b128 v[200:203], v171 offset:53248
	ds_read_b128 v[204:207], v171 offset:54272
	ds_read_b128 v[208:211], v171 offset:55296
	ds_read_b128 v[212:215], v171 offset:56320
	global_load_lds_dwordx4 v[164:165], off
	s_add_i32 m0, s40, 0x2000
	s_add_u32 s38, s38, 0x40080
	v_lshl_add_u64 v[164:165], v[216:217], 0, s[6:7]
	s_addc_u32 s39, s39, 0
	s_add_i32 s40, s69, s45
	global_load_lds_dwordx4 v[164:165], off
	v_lshl_add_u64 v[164:165], s[38:39], 0, v[146:147]
	s_mov_b32 m0, s40
	s_nop 0
	global_load_lds_dwordx4 v[164:165], off
	v_lshl_add_u64 v[164:165], s[38:39], 0, v[150:151]
	s_add_i32 m0, s40, 0x2000
	s_nop 0
	global_load_lds_dwordx4 v[164:165], off
	v_lshl_add_u64 v[164:165], v[218:219], 0, s[6:7]
	s_mov_b32 m0, s56
	s_nop 0
	global_load_lds_dwordx4 v[164:165], off
	v_lshl_add_u64 v[164:165], v[220:221], 0, s[6:7]
	s_mov_b32 m0, s57
	s_nop 0
	global_load_lds_dwordx4 v[164:165], off
	s_waitcnt vmcnt(8)
	s_waitcnt lgkmcnt(0)
	s_barrier
	s_waitcnt lgkmcnt(0)
	v_mfma_f32_16x16x32_bf16 v[60:63], v[128:131], v[184:187], v[60:63]
	v_mfma_f32_16x16x32_bf16 v[56:59], v[136:139], v[184:187], v[56:59]
	v_mfma_f32_16x16x32_bf16 v[52:55], v[128:131], v[192:195], v[52:55]
	v_mfma_f32_16x16x32_bf16 v[48:51], v[136:139], v[192:195], v[48:51]
	v_mfma_f32_16x16x32_bf16 v[36:39], v[128:131], v[200:203], v[36:39]
	v_mfma_f32_16x16x32_bf16 v[24:27], v[136:139], v[200:203], v[24:27]
	v_mfma_f32_16x16x32_bf16 v[20:23], v[128:131], v[208:211], v[20:23]
	v_mfma_f32_16x16x32_bf16 v[12:15], v[136:139], v[208:211], v[12:15]
	v_mfma_f32_16x16x32_bf16 v[60:63], v[132:135], v[188:191], v[60:63]
	v_mfma_f32_16x16x32_bf16 v[56:59], v[140:143], v[188:191], v[56:59]
	v_mfma_f32_16x16x32_bf16 v[52:55], v[132:135], v[196:199], v[52:55]
	v_mfma_f32_16x16x32_bf16 v[48:51], v[140:143], v[196:199], v[48:51]
	v_mfma_f32_16x16x32_bf16 v[36:39], v[132:135], v[204:207], v[36:39]
	v_mfma_f32_16x16x32_bf16 v[24:27], v[140:143], v[204:207], v[24:27]
	v_mfma_f32_16x16x32_bf16 v[20:23], v[132:135], v[212:215], v[20:23]
	v_mfma_f32_16x16x32_bf16 v[12:15], v[140:143], v[212:215], v[12:15]
	v_mfma_f32_16x16x32_bf16 v[44:47], v[160:163], v[184:187], v[44:47]
	v_mfma_f32_16x16x32_bf16 v[40:43], v[176:179], v[184:187], v[40:43]
	v_mfma_f32_16x16x32_bf16 v[32:35], v[160:163], v[192:195], v[32:35]
	v_mfma_f32_16x16x32_bf16 v[28:31], v[176:179], v[192:195], v[28:31]
	v_mfma_f32_16x16x32_bf16 v[16:19], v[160:163], v[200:203], v[16:19]
	v_mfma_f32_16x16x32_bf16 v[8:11], v[176:179], v[200:203], v[8:11]
	v_mfma_f32_16x16x32_bf16 v[4:7], v[160:163], v[208:211], v[4:7]
	v_mfma_f32_16x16x32_bf16 v[0:3], v[176:179], v[208:211], v[0:3]
	v_mfma_f32_16x16x32_bf16 v[44:47], v[172:175], v[188:191], v[44:47]
	v_mfma_f32_16x16x32_bf16 v[40:43], v[180:183], v[188:191], v[40:43]
	v_mfma_f32_16x16x32_bf16 v[32:35], v[172:175], v[196:199], v[32:35]
	v_mfma_f32_16x16x32_bf16 v[28:31], v[180:183], v[196:199], v[28:31]
	v_mfma_f32_16x16x32_bf16 v[16:19], v[172:175], v[204:207], v[16:19]
	v_mfma_f32_16x16x32_bf16 v[8:11], v[180:183], v[204:207], v[8:11]
	v_mfma_f32_16x16x32_bf16 v[4:7], v[172:175], v[212:215], v[4:7]
	v_mfma_f32_16x16x32_bf16 v[0:3], v[180:183], v[212:215], v[0:3]
	s_barrier
	s_add_i32 s65, s65, 2
	s_add_u32 s34, s34, 0x100
	s_addc_u32 s35, s35, 0
	s_add_u32 s63, s63, 0x100
	s_addc_u32 s64, s64, 0
	s_branch .LBB0_457
